# hoist 8 serialized row-scale loads in in-proj epilogue (one wait)
# baseline (speedup 1.0000x reference)
.LBB0_147:
	v_lshl_add_u32 v148, s21, 8, v154
	v_lshl_add_u32 v144, s20, 8, v152
	v_ashrrev_i32_e32 v149, 31, v148
	v_mov_b64_e32 v[146:147], s[52:53]
	v_ashrrev_i32_e32 v145, 31, v144
	v_mad_i64_i32 v[150:151], s[20:21], v144, s44, v[146:147]
	v_lshlrev_b64 v[148:149], 1, v[148:149]
	v_lshl_add_u64 v[158:159], v[150:151], 0, v[148:149]
	v_lshl_add_u64 v[150:151], v[144:145], 2, s[88:89]
	global_load_dword v160, v[150:151], off
	global_load_dword v236, v[150:151], off offset:64
	global_load_dword v237, v[150:151], off offset:128
	global_load_dword v238, v[150:151], off offset:192
	global_load_dword v239, v[150:151], off offset:512
	global_load_dword v240, v[150:151], off offset:576
	global_load_dword v241, v[150:151], off offset:640
	global_load_dword v242, v[150:151], off offset:704
	s_andn2_b64 vcc, exec, s[0:1]
	s_waitcnt vmcnt(0)
	v_pk_mul_f32 v[126:127], v[126:127], v[160:161] op_sel_hi:[1,0]
	v_pk_mul_f32 v[124:125], v[124:125], v[160:161] op_sel_hi:[1,0]
	v_pk_mul_f32 v[162:163], v[122:123], v[160:161] op_sel_hi:[1,0]
	v_pk_mul_f32 v[122:123], v[120:121], v[160:161] op_sel_hi:[1,0]
	v_cvt_pk_bf16_f32 v120, v124, v125
	v_cvt_pk_bf16_f32 v121, v126, v127
	v_pk_mul_f32 v[116:117], v[116:117], v[160:161] op_sel_hi:[1,0]
	v_cvt_pk_bf16_f32 v122, v122, v123
	v_cvt_pk_bf16_f32 v123, v162, v163
	global_store_dwordx4 v[158:159], v[120:123], off
	v_pk_mul_f32 v[118:119], v[118:119], v[160:161] op_sel_hi:[1,0]
	s_nop 0
	v_pk_mul_f32 v[120:121], v[114:115], v[160:161] op_sel_hi:[1,0]
	v_pk_mul_f32 v[114:115], v[112:113], v[160:161] op_sel_hi:[1,0]
	v_cvt_pk_bf16_f32 v112, v116, v117
	v_cvt_pk_bf16_f32 v113, v118, v119
	s_nop 0
	v_cvt_pk_bf16_f32 v114, v114, v115
	v_cvt_pk_bf16_f32 v115, v120, v121
	global_store_dwordx4 v[158:159], v[112:115], off offset:256
	s_nop 1
	v_or_b32_e32 v112, 16, v144
	v_ashrrev_i32_e32 v113, 31, v112
	v_mad_i64_i32 v[114:115], s[20:21], v112, s44, v[146:147]
	v_lshl_add_u64 v[112:113], v[112:113], 2, s[88:89]
	v_lshl_add_u64 v[114:115], v[114:115], 0, v[148:149]
	s_nop 1
	v_mov_b32_e32 v112, v236
	v_pk_mul_f32 v[110:111], v[110:111], v[112:113] op_sel_hi:[1,0]
	v_pk_mul_f32 v[108:109], v[108:109], v[112:113] op_sel_hi:[1,0]
	v_pk_mul_f32 v[116:117], v[106:107], v[112:113] op_sel_hi:[1,0]
	v_pk_mul_f32 v[106:107], v[104:105], v[112:113] op_sel_hi:[1,0]
	v_cvt_pk_bf16_f32 v104, v108, v109
	v_cvt_pk_bf16_f32 v105, v110, v111
	v_pk_mul_f32 v[100:101], v[100:101], v[112:113] op_sel_hi:[1,0]
	v_cvt_pk_bf16_f32 v106, v106, v107
	v_cvt_pk_bf16_f32 v107, v116, v117
	global_store_dwordx4 v[114:115], v[104:107], off
	v_pk_mul_f32 v[102:103], v[102:103], v[112:113] op_sel_hi:[1,0]
	s_nop 0
	v_pk_mul_f32 v[104:105], v[98:99], v[112:113] op_sel_hi:[1,0]
	v_pk_mul_f32 v[98:99], v[96:97], v[112:113] op_sel_hi:[1,0]
	v_cvt_pk_bf16_f32 v96, v100, v101
	v_cvt_pk_bf16_f32 v97, v102, v103
	s_nop 0
	v_cvt_pk_bf16_f32 v98, v98, v99
	v_cvt_pk_bf16_f32 v99, v104, v105
	global_store_dwordx4 v[114:115], v[96:99], off offset:256
	s_nop 1
	v_or_b32_e32 v96, 32, v144
	v_ashrrev_i32_e32 v97, 31, v96
	v_mad_i64_i32 v[98:99], s[20:21], v96, s44, v[146:147]
	v_lshl_add_u64 v[96:97], v[96:97], 2, s[88:89]
	v_lshl_add_u64 v[98:99], v[98:99], 0, v[148:149]
	s_nop 1
	v_mov_b32_e32 v96, v237
	v_pk_mul_f32 v[94:95], v[94:95], v[96:97] op_sel_hi:[1,0]
	v_pk_mul_f32 v[92:93], v[92:93], v[96:97] op_sel_hi:[1,0]
	v_pk_mul_f32 v[100:101], v[90:91], v[96:97] op_sel_hi:[1,0]
	v_pk_mul_f32 v[90:91], v[88:89], v[96:97] op_sel_hi:[1,0]
	v_cvt_pk_bf16_f32 v88, v92, v93
	v_cvt_pk_bf16_f32 v89, v94, v95
	v_pk_mul_f32 v[84:85], v[84:85], v[96:97] op_sel_hi:[1,0]
	v_cvt_pk_bf16_f32 v90, v90, v91
	v_cvt_pk_bf16_f32 v91, v100, v101
	global_store_dwordx4 v[98:99], v[88:91], off
	v_pk_mul_f32 v[86:87], v[86:87], v[96:97] op_sel_hi:[1,0]
	s_nop 0
	v_pk_mul_f32 v[88:89], v[82:83], v[96:97] op_sel_hi:[1,0]
	v_pk_mul_f32 v[82:83], v[80:81], v[96:97] op_sel_hi:[1,0]
	v_cvt_pk_bf16_f32 v80, v84, v85
	v_cvt_pk_bf16_f32 v81, v86, v87
	s_nop 0
	v_cvt_pk_bf16_f32 v82, v82, v83
	v_cvt_pk_bf16_f32 v83, v88, v89
	global_store_dwordx4 v[98:99], v[80:83], off offset:256
	s_nop 1
	v_or_b32_e32 v80, 48, v144
	v_ashrrev_i32_e32 v81, 31, v80
	v_mad_i64_i32 v[82:83], s[20:21], v80, s44, v[146:147]
	v_lshl_add_u64 v[80:81], v[80:81], 2, s[88:89]
	v_lshl_add_u64 v[82:83], v[82:83], 0, v[148:149]
	s_nop 1
	v_mov_b32_e32 v80, v238
	v_pk_mul_f32 v[78:79], v[78:79], v[80:81] op_sel_hi:[1,0]
	v_pk_mul_f32 v[76:77], v[76:77], v[80:81] op_sel_hi:[1,0]
	v_pk_mul_f32 v[84:85], v[74:75], v[80:81] op_sel_hi:[1,0]
	v_pk_mul_f32 v[74:75], v[72:73], v[80:81] op_sel_hi:[1,0]
	v_cvt_pk_bf16_f32 v72, v76, v77
	v_cvt_pk_bf16_f32 v73, v78, v79
	v_pk_mul_f32 v[70:71], v[70:71], v[80:81] op_sel_hi:[1,0]
	v_cvt_pk_bf16_f32 v74, v74, v75
	v_cvt_pk_bf16_f32 v75, v84, v85
	global_store_dwordx4 v[82:83], v[72:75], off
	v_pk_mul_f32 v[68:69], v[68:69], v[80:81] op_sel_hi:[1,0]
	s_nop 0
	v_pk_mul_f32 v[72:73], v[66:67], v[80:81] op_sel_hi:[1,0]
	v_pk_mul_f32 v[66:67], v[64:65], v[80:81] op_sel_hi:[1,0]
	v_cvt_pk_bf16_f32 v64, v68, v69
	v_cvt_pk_bf16_f32 v65, v70, v71
	s_nop 0
	v_cvt_pk_bf16_f32 v66, v66, v67
	v_cvt_pk_bf16_f32 v67, v72, v73
	global_store_dwordx4 v[82:83], v[64:67], off offset:256
	s_nop 1
	v_mov_b32_e32 v66, v239
	v_pk_mul_f32 v[62:63], v[62:63], v[66:67] op_sel_hi:[1,0]
	v_add_u32_e32 v64, 0x80, v144
	v_mad_i64_i32 v[64:65], s[20:21], v64, s44, v[146:147]
	v_lshl_add_u64 v[64:65], v[64:65], 0, v[148:149]
	v_pk_mul_f32 v[60:61], v[60:61], v[66:67] op_sel_hi:[1,0]
	v_pk_mul_f32 v[68:69], v[58:59], v[66:67] op_sel_hi:[1,0]
	v_pk_mul_f32 v[58:59], v[56:57], v[66:67] op_sel_hi:[1,0]
	v_cvt_pk_bf16_f32 v56, v60, v61
	v_cvt_pk_bf16_f32 v57, v62, v63
	v_pk_mul_f32 v[54:55], v[54:55], v[66:67] op_sel_hi:[1,0]
	v_cvt_pk_bf16_f32 v58, v58, v59
	v_cvt_pk_bf16_f32 v59, v68, v69
	global_store_dwordx4 v[64:65], v[56:59], off
	v_pk_mul_f32 v[52:53], v[52:53], v[66:67] op_sel_hi:[1,0]
	s_nop 0
	v_pk_mul_f32 v[56:57], v[50:51], v[66:67] op_sel_hi:[1,0]
	v_pk_mul_f32 v[50:51], v[48:49], v[66:67] op_sel_hi:[1,0]
	v_cvt_pk_bf16_f32 v48, v52, v53
	v_cvt_pk_bf16_f32 v49, v54, v55
	s_nop 0
	v_cvt_pk_bf16_f32 v50, v50, v51
	v_cvt_pk_bf16_f32 v51, v56, v57
	global_store_dwordx4 v[64:65], v[48:51], off offset:256
	s_nop 1
	v_mov_b32_e32 v50, v240
	v_pk_mul_f32 v[46:47], v[46:47], v[50:51] op_sel_hi:[1,0]
	v_add_u32_e32 v48, 0x90, v144
	v_mad_i64_i32 v[48:49], s[20:21], v48, s44, v[146:147]
	v_lshl_add_u64 v[48:49], v[48:49], 0, v[148:149]
	v_pk_mul_f32 v[44:45], v[44:45], v[50:51] op_sel_hi:[1,0]
	v_pk_mul_f32 v[52:53], v[42:43], v[50:51] op_sel_hi:[1,0]
	v_pk_mul_f32 v[42:43], v[40:41], v[50:51] op_sel_hi:[1,0]
	v_cvt_pk_bf16_f32 v40, v44, v45
	v_cvt_pk_bf16_f32 v41, v46, v47
	v_pk_mul_f32 v[38:39], v[38:39], v[50:51] op_sel_hi:[1,0]
	v_cvt_pk_bf16_f32 v42, v42, v43
	v_cvt_pk_bf16_f32 v43, v52, v53
	global_store_dwordx4 v[48:49], v[40:43], off
	v_pk_mul_f32 v[36:37], v[36:37], v[50:51] op_sel_hi:[1,0]
	s_nop 0
	v_pk_mul_f32 v[40:41], v[34:35], v[50:51] op_sel_hi:[1,0]
	v_pk_mul_f32 v[34:35], v[32:33], v[50:51] op_sel_hi:[1,0]
	v_cvt_pk_bf16_f32 v32, v36, v37
	v_cvt_pk_bf16_f32 v33, v38, v39
	s_nop 0
	v_cvt_pk_bf16_f32 v34, v34, v35
	v_cvt_pk_bf16_f32 v35, v40, v41
	global_store_dwordx4 v[48:49], v[32:35], off offset:256
	s_nop 1
	v_mov_b32_e32 v34, v241
	v_pk_mul_f32 v[30:31], v[30:31], v[34:35] op_sel_hi:[1,0]
	v_add_u32_e32 v32, 0xa0, v144
	v_mad_i64_i32 v[32:33], s[20:21], v32, s44, v[146:147]
	v_lshl_add_u64 v[32:33], v[32:33], 0, v[148:149]
	v_pk_mul_f32 v[28:29], v[28:29], v[34:35] op_sel_hi:[1,0]
	v_pk_mul_f32 v[36:37], v[26:27], v[34:35] op_sel_hi:[1,0]
	v_pk_mul_f32 v[26:27], v[24:25], v[34:35] op_sel_hi:[1,0]
	v_cvt_pk_bf16_f32 v24, v28, v29
	v_cvt_pk_bf16_f32 v25, v30, v31
	v_pk_mul_f32 v[22:23], v[22:23], v[34:35] op_sel_hi:[1,0]
	v_cvt_pk_bf16_f32 v26, v26, v27
	v_cvt_pk_bf16_f32 v27, v36, v37
	global_store_dwordx4 v[32:33], v[24:27], off
	v_pk_mul_f32 v[20:21], v[20:21], v[34:35] op_sel_hi:[1,0]
	s_nop 0
	v_pk_mul_f32 v[24:25], v[18:19], v[34:35] op_sel_hi:[1,0]
	v_pk_mul_f32 v[18:19], v[16:17], v[34:35] op_sel_hi:[1,0]
	v_cvt_pk_bf16_f32 v16, v20, v21
	v_cvt_pk_bf16_f32 v17, v22, v23
	s_nop 0
	v_cvt_pk_bf16_f32 v18, v18, v19
	v_cvt_pk_bf16_f32 v19, v24, v25
	global_store_dwordx4 v[32:33], v[16:19], off offset:256
	s_nop 1
	v_mov_b32_e32 v18, v242
	v_pk_mul_f32 v[14:15], v[14:15], v[18:19] op_sel_hi:[1,0]
	v_add_u32_e32 v16, 0xb0, v144
	v_mad_i64_i32 v[16:17], s[20:21], v16, s44, v[146:147]
	v_lshl_add_u64 v[16:17], v[16:17], 0, v[148:149]
	v_pk_mul_f32 v[12:13], v[12:13], v[18:19] op_sel_hi:[1,0]
	v_pk_mul_f32 v[20:21], v[10:11], v[18:19] op_sel_hi:[1,0]
	v_pk_mul_f32 v[10:11], v[8:9], v[18:19] op_sel_hi:[1,0]
	v_cvt_pk_bf16_f32 v8, v12, v13
	v_cvt_pk_bf16_f32 v9, v14, v15
	s_mov_b64 s[20:21], -1
	v_cvt_pk_bf16_f32 v10, v10, v11
	v_cvt_pk_bf16_f32 v11, v20, v21
	global_store_dwordx4 v[16:17], v[8:11], off
	v_pk_mul_f32 v[6:7], v[6:7], v[18:19] op_sel_hi:[1,0]
	v_pk_mul_f32 v[4:5], v[4:5], v[18:19] op_sel_hi:[1,0]
	v_pk_mul_f32 v[8:9], v[2:3], v[18:19] op_sel_hi:[1,0]
	v_pk_mul_f32 v[2:3], v[0:1], v[18:19] op_sel_hi:[1,0]
	v_cvt_pk_bf16_f32 v0, v4, v5
	v_cvt_pk_bf16_f32 v1, v6, v7
	s_nop 0
	v_cvt_pk_bf16_f32 v2, v2, v3
	v_cvt_pk_bf16_f32 v3, v8, v9
	global_store_dwordx4 v[16:17], v[0:3], off offset:256
	s_cbranch_vccnz .LBB0_138
	s_andn2_b64 vcc, exec, s[6:7]
	s_cbranch_vccnz .LBB0_137
	s_barrier
	s_branch .LBB0_137

.LBB0_213:
	v_lshl_add_u32 v128, s4, 8, v141
	v_ashrrev_i32_e32 v129, 31, v128
	v_lshl_add_u64 v[130:131], v[128:129], 2, s[88:89]
	global_load_dword v136, v[130:131], off
	global_load_dword v236, v[130:131], off offset:64
	global_load_dword v237, v[130:131], off offset:128
	global_load_dword v238, v[130:131], off offset:192
	global_load_dword v239, v[130:131], off offset:512
	global_load_dword v240, v[130:131], off offset:576
	global_load_dword v241, v[130:131], off offset:640
	global_load_dword v242, v[130:131], off offset:704
	v_ashrrev_i32_e32 v129, 1, v140
	s_lshl_b32 s1, s0, 8
	v_readlane_b32 s4, v235, 37
	v_and_b32_e32 v129, -8, v129
	s_or_b32 s1, s4, s1
	v_add_u32_e32 v134, s1, v129
	s_movk_i32 s0, 0x1040
	v_mov_b64_e32 v[132:133], s[52:53]
	v_ashrrev_i32_e32 v135, 31, v134
	v_mad_i64_i32 v[138:139], s[4:5], v128, s0, v[132:133]
	v_or_b32_e32 v140, 16, v128
	v_lshlrev_b64 v[134:135], 1, v[134:135]
	v_ashrrev_i32_e32 v141, 31, v140
	v_lshl_add_u64 v[138:139], v[138:139], 0, v[134:135]
	v_lshl_add_u64 v[142:143], v[140:141], 2, s[88:89]
	s_movk_i32 s1, 0x80
	v_writelane_b32 v235, s1, 45
	s_waitcnt vmcnt(0)
	v_pk_mul_f32 v[126:127], v[126:127], v[136:137] op_sel_hi:[1,0]
	v_pk_mul_f32 v[124:125], v[124:125], v[136:137] op_sel_hi:[1,0]
	v_pk_mul_f32 v[122:123], v[122:123], v[136:137] op_sel_hi:[1,0]
	v_pk_mul_f32 v[120:121], v[120:121], v[136:137] op_sel_hi:[1,0]
	v_pk_mul_f32 v[118:119], v[118:119], v[136:137] op_sel_hi:[1,0]
	v_pk_mul_f32 v[116:117], v[116:117], v[136:137] op_sel_hi:[1,0]
	v_pk_mul_f32 v[144:145], v[114:115], v[136:137] op_sel_hi:[1,0]
	v_pk_mul_f32 v[136:137], v[112:113], v[136:137] op_sel_hi:[1,0]
	v_cvt_pk_bf16_f32 v112, v124, v125
	v_cvt_pk_bf16_f32 v113, v126, v127
	v_cvt_pk_bf16_f32 v114, v120, v121
	v_cvt_pk_bf16_f32 v115, v122, v123
	global_store_dwordx4 v[138:139], v[112:115], off
	s_nop 1
	v_cvt_pk_bf16_f32 v112, v116, v117
	v_cvt_pk_bf16_f32 v113, v118, v119
	v_cvt_pk_bf16_f32 v114, v136, v137
	v_cvt_pk_bf16_f32 v115, v144, v145
	global_store_dwordx4 v[138:139], v[112:115], off offset:256
	v_mad_i64_i32 v[116:117], s[4:5], v140, s0, v[132:133]
	v_or_b32_e32 v114, 32, v128
	v_ashrrev_i32_e32 v115, 31, v114
	v_lshl_add_u64 v[116:117], v[116:117], 0, v[134:135]
	v_lshl_add_u64 v[118:119], v[114:115], 2, s[88:89]
	s_nop 1
	v_mov_b32_e32 v112, v236
	v_pk_mul_f32 v[110:111], v[110:111], v[112:113] op_sel_hi:[1,0]
	v_pk_mul_f32 v[108:109], v[108:109], v[112:113] op_sel_hi:[1,0]
	v_pk_mul_f32 v[106:107], v[106:107], v[112:113] op_sel_hi:[1,0]
	v_pk_mul_f32 v[104:105], v[104:105], v[112:113] op_sel_hi:[1,0]
	v_pk_mul_f32 v[102:103], v[102:103], v[112:113] op_sel_hi:[1,0]
	v_pk_mul_f32 v[100:101], v[100:101], v[112:113] op_sel_hi:[1,0]
	v_pk_mul_f32 v[120:121], v[98:99], v[112:113] op_sel_hi:[1,0]
	v_pk_mul_f32 v[112:113], v[96:97], v[112:113] op_sel_hi:[1,0]
	v_cvt_pk_bf16_f32 v96, v108, v109
	v_cvt_pk_bf16_f32 v97, v110, v111
	v_cvt_pk_bf16_f32 v98, v104, v105
	v_cvt_pk_bf16_f32 v99, v106, v107
	global_store_dwordx4 v[116:117], v[96:99], off
	s_nop 1
	v_cvt_pk_bf16_f32 v96, v100, v101
	v_cvt_pk_bf16_f32 v97, v102, v103
	v_cvt_pk_bf16_f32 v98, v112, v113
	v_cvt_pk_bf16_f32 v99, v120, v121
	global_store_dwordx4 v[116:117], v[96:99], off offset:256
	v_mad_i64_i32 v[100:101], s[4:5], v114, s0, v[132:133]
	v_or_b32_e32 v98, 48, v128
	v_ashrrev_i32_e32 v99, 31, v98
	v_lshl_add_u64 v[100:101], v[100:101], 0, v[134:135]
	v_lshl_add_u64 v[102:103], v[98:99], 2, s[88:89]
	s_nop 1
	v_mov_b32_e32 v96, v237
	v_pk_mul_f32 v[94:95], v[94:95], v[96:97] op_sel_hi:[1,0]
	v_pk_mul_f32 v[92:93], v[92:93], v[96:97] op_sel_hi:[1,0]
	v_pk_mul_f32 v[90:91], v[90:91], v[96:97] op_sel_hi:[1,0]
	v_pk_mul_f32 v[88:89], v[88:89], v[96:97] op_sel_hi:[1,0]
	v_pk_mul_f32 v[82:83], v[82:83], v[96:97] op_sel_hi:[1,0]
	v_pk_mul_f32 v[80:81], v[80:81], v[96:97] op_sel_hi:[1,0]
	v_pk_mul_f32 v[104:105], v[74:75], v[96:97] op_sel_hi:[1,0]
	v_pk_mul_f32 v[96:97], v[72:73], v[96:97] op_sel_hi:[1,0]
	v_cvt_pk_bf16_f32 v72, v92, v93
	v_cvt_pk_bf16_f32 v73, v94, v95
	v_cvt_pk_bf16_f32 v74, v88, v89
	v_cvt_pk_bf16_f32 v75, v90, v91
	global_store_dwordx4 v[100:101], v[72:75], off
	s_nop 1
	v_cvt_pk_bf16_f32 v72, v80, v81
	v_cvt_pk_bf16_f32 v73, v82, v83
	v_cvt_pk_bf16_f32 v74, v96, v97
	v_cvt_pk_bf16_f32 v75, v104, v105
	global_store_dwordx4 v[100:101], v[72:75], off offset:256
	s_nop 1
	v_mov_b32_e32 v72, v238
	v_pk_mul_f32 v[80:81], v[86:87], v[72:73] op_sel_hi:[1,0]
	v_mad_i64_i32 v[74:75], s[4:5], v98, s0, v[132:133]
	v_lshl_add_u64 v[74:75], v[74:75], 0, v[134:135]
	v_pk_mul_f32 v[82:83], v[84:85], v[72:73] op_sel_hi:[1,0]
	v_pk_mul_f32 v[78:79], v[78:79], v[72:73] op_sel_hi:[1,0]
	v_pk_mul_f32 v[76:77], v[76:77], v[72:73] op_sel_hi:[1,0]
	v_pk_mul_f32 v[70:71], v[70:71], v[72:73] op_sel_hi:[1,0]
	v_pk_mul_f32 v[68:69], v[68:69], v[72:73] op_sel_hi:[1,0]
	v_pk_mul_f32 v[84:85], v[66:67], v[72:73] op_sel_hi:[1,0]
	v_pk_mul_f32 v[72:73], v[64:65], v[72:73] op_sel_hi:[1,0]
	v_cvt_pk_bf16_f32 v64, v82, v83
	v_cvt_pk_bf16_f32 v65, v80, v81
	v_cvt_pk_bf16_f32 v66, v76, v77
	v_cvt_pk_bf16_f32 v67, v78, v79
	global_store_dwordx4 v[74:75], v[64:67], off
	s_nop 1
	v_cvt_pk_bf16_f32 v64, v68, v69
	v_cvt_pk_bf16_f32 v65, v70, v71
	v_cvt_pk_bf16_f32 v66, v72, v73
	v_cvt_pk_bf16_f32 v67, v84, v85
	global_store_dwordx4 v[74:75], v[64:67], off offset:256
	s_nop 0
	v_add_u32_e32 v65, 0x80, v128
	v_mad_i64_i32 v[66:67], s[4:5], v65, s0, v[132:133]
	v_lshl_add_u64 v[66:67], v[66:67], 0, v[134:135]
	s_nop 1
	v_mov_b32_e32 v64, v239
	v_pk_mul_f32 v[62:63], v[62:63], v[64:65] op_sel_hi:[1,0]
	v_pk_mul_f32 v[60:61], v[60:61], v[64:65] op_sel_hi:[1,0]
	v_pk_mul_f32 v[58:59], v[58:59], v[64:65] op_sel_hi:[1,0]
	v_pk_mul_f32 v[56:57], v[56:57], v[64:65] op_sel_hi:[1,0]
	v_pk_mul_f32 v[54:55], v[54:55], v[64:65] op_sel_hi:[1,0]
	v_pk_mul_f32 v[52:53], v[52:53], v[64:65] op_sel_hi:[1,0]
	v_pk_mul_f32 v[68:69], v[50:51], v[64:65] op_sel_hi:[1,0]
	v_pk_mul_f32 v[64:65], v[48:49], v[64:65] op_sel_hi:[1,0]
	v_cvt_pk_bf16_f32 v48, v60, v61
	v_cvt_pk_bf16_f32 v49, v62, v63
	v_cvt_pk_bf16_f32 v50, v56, v57
	v_cvt_pk_bf16_f32 v51, v58, v59
	global_store_dwordx4 v[66:67], v[48:51], off
	s_nop 1
	v_cvt_pk_bf16_f32 v48, v52, v53
	v_cvt_pk_bf16_f32 v49, v54, v55
	v_cvt_pk_bf16_f32 v50, v64, v65
	v_cvt_pk_bf16_f32 v51, v68, v69
	global_store_dwordx4 v[66:67], v[48:51], off offset:256
	s_nop 0
	v_add_u32_e32 v49, 0x90, v128
	v_mad_i64_i32 v[50:51], s[4:5], v49, s0, v[132:133]
	v_lshl_add_u64 v[50:51], v[50:51], 0, v[134:135]
	s_nop 1
	v_mov_b32_e32 v48, v240
	v_pk_mul_f32 v[46:47], v[46:47], v[48:49] op_sel_hi:[1,0]
	v_pk_mul_f32 v[44:45], v[44:45], v[48:49] op_sel_hi:[1,0]
	v_pk_mul_f32 v[42:43], v[42:43], v[48:49] op_sel_hi:[1,0]
	v_pk_mul_f32 v[40:41], v[40:41], v[48:49] op_sel_hi:[1,0]
	v_pk_mul_f32 v[38:39], v[38:39], v[48:49] op_sel_hi:[1,0]
	v_pk_mul_f32 v[36:37], v[36:37], v[48:49] op_sel_hi:[1,0]
	v_pk_mul_f32 v[52:53], v[34:35], v[48:49] op_sel_hi:[1,0]
	v_pk_mul_f32 v[48:49], v[32:33], v[48:49] op_sel_hi:[1,0]
	v_cvt_pk_bf16_f32 v32, v44, v45
	v_cvt_pk_bf16_f32 v33, v46, v47
	v_cvt_pk_bf16_f32 v34, v40, v41
	v_cvt_pk_bf16_f32 v35, v42, v43
	global_store_dwordx4 v[50:51], v[32:35], off
	s_nop 1
	v_cvt_pk_bf16_f32 v32, v36, v37
	v_cvt_pk_bf16_f32 v33, v38, v39
	v_cvt_pk_bf16_f32 v34, v48, v49
	v_cvt_pk_bf16_f32 v35, v52, v53
	global_store_dwordx4 v[50:51], v[32:35], off offset:256
	s_nop 0
	v_add_u32_e32 v33, 0xa0, v128
	v_mad_i64_i32 v[34:35], s[4:5], v33, s0, v[132:133]
	v_lshl_add_u64 v[34:35], v[34:35], 0, v[134:135]
	s_nop 1
	v_mov_b32_e32 v32, v241
	v_pk_mul_f32 v[30:31], v[30:31], v[32:33] op_sel_hi:[1,0]
	v_pk_mul_f32 v[28:29], v[28:29], v[32:33] op_sel_hi:[1,0]
	v_pk_mul_f32 v[26:27], v[26:27], v[32:33] op_sel_hi:[1,0]
	v_pk_mul_f32 v[24:25], v[24:25], v[32:33] op_sel_hi:[1,0]
	v_pk_mul_f32 v[22:23], v[22:23], v[32:33] op_sel_hi:[1,0]
	v_pk_mul_f32 v[20:21], v[20:21], v[32:33] op_sel_hi:[1,0]
	v_pk_mul_f32 v[36:37], v[18:19], v[32:33] op_sel_hi:[1,0]
	v_pk_mul_f32 v[32:33], v[16:17], v[32:33] op_sel_hi:[1,0]
	v_cvt_pk_bf16_f32 v16, v28, v29
	v_cvt_pk_bf16_f32 v17, v30, v31
	v_cvt_pk_bf16_f32 v18, v24, v25
	v_cvt_pk_bf16_f32 v19, v26, v27
	global_store_dwordx4 v[34:35], v[16:19], off
	s_nop 1
	v_cvt_pk_bf16_f32 v16, v20, v21
	v_cvt_pk_bf16_f32 v17, v22, v23
	v_cvt_pk_bf16_f32 v18, v32, v33
	v_cvt_pk_bf16_f32 v19, v36, v37
	global_store_dwordx4 v[34:35], v[16:19], off offset:256
	s_nop 0
	v_add_u32_e32 v17, 0xb0, v128
	v_mad_i64_i32 v[18:19], s[0:1], v17, s0, v[132:133]
	v_lshl_add_u64 v[18:19], v[18:19], 0, v[134:135]
	v_readlane_b32 s0, v235, 41
	v_readlane_b32 s1, v235, 42
	s_and_b64 vcc, exec, s[0:1]
	s_nop 1
	v_mov_b32_e32 v16, v242
	v_pk_mul_f32 v[14:15], v[14:15], v[16:17] op_sel_hi:[1,0]
	v_pk_mul_f32 v[12:13], v[12:13], v[16:17] op_sel_hi:[1,0]
	v_pk_mul_f32 v[10:11], v[10:11], v[16:17] op_sel_hi:[1,0]
	v_pk_mul_f32 v[8:9], v[8:9], v[16:17] op_sel_hi:[1,0]
	v_pk_mul_f32 v[6:7], v[6:7], v[16:17] op_sel_hi:[1,0]
	v_pk_mul_f32 v[4:5], v[4:5], v[16:17] op_sel_hi:[1,0]
	v_pk_mul_f32 v[20:21], v[2:3], v[16:17] op_sel_hi:[1,0]
	v_pk_mul_f32 v[16:17], v[0:1], v[16:17] op_sel_hi:[1,0]
	v_cvt_pk_bf16_f32 v0, v12, v13
	v_cvt_pk_bf16_f32 v1, v14, v15
	v_cvt_pk_bf16_f32 v2, v8, v9
	v_cvt_pk_bf16_f32 v3, v10, v11
	global_store_dwordx4 v[18:19], v[0:3], off
	s_nop 1
	v_cvt_pk_bf16_f32 v0, v4, v5
	v_cvt_pk_bf16_f32 v1, v6, v7
	v_cvt_pk_bf16_f32 v2, v16, v17
	v_cvt_pk_bf16_f32 v3, v20, v21
	global_store_dwordx4 v[18:19], v[0:3], off offset:256
	s_waitcnt vmcnt(0)
	s_barrier
	s_waitcnt vmcnt(0)
	s_barrier
	s_cbranch_vccnz .LBB0_228
	v_mbcnt_lo_u32_b32 v0, -1, 0
	v_mbcnt_hi_u32_b32 v0, -1, v0
	s_nop 0
	v_cmp_eq_u32_e32 vcc, 0, v0
	s_and_saveexec_b64 s[0:1], vcc
	s_cbranch_execz .LBB0_227
	s_mov_b64 s[6:7], exec
	buffer_wbl2 sc1
	s_waitcnt vmcnt(0)
	s_waitcnt vmcnt(0)
	v_mbcnt_lo_u32_b32 v0, s6, 0
	s_add_u32 s4, s78, 0x3700
	v_mbcnt_hi_u32_b32 v0, s7, v0
	s_addc_u32 s5, s79, 0
	v_cmp_eq_u32_e32 vcc, 0, v0
	s_and_saveexec_b64 s[8:9], vcc
	s_cbranch_execz .LBB0_217
	s_bcnt1_i32_b64 s6, s[6:7]
	v_mov_b32_e32 v0, 0
	v_mov_b32_e32 v1, s6
	global_atomic_add v0, v1, s[4:5]

.LBB0_856:
	v_lshl_add_u32 v148, s19, 8, v154
	v_lshl_add_u32 v144, s18, 8, v152
	v_ashrrev_i32_e32 v149, 31, v148
	v_mov_b64_e32 v[146:147], s[52:53]
	v_ashrrev_i32_e32 v145, 31, v144
	v_mad_i64_i32 v[150:151], s[18:19], v144, s39, v[146:147]
	v_lshlrev_b64 v[148:149], 1, v[148:149]
	v_lshl_add_u64 v[158:159], v[150:151], 0, v[148:149]
	v_lshl_add_u64 v[150:151], v[144:145], 2, s[88:89]
	global_load_dword v160, v[150:151], off
	global_load_dword v236, v[150:151], off offset:64
	global_load_dword v237, v[150:151], off offset:128
	global_load_dword v238, v[150:151], off offset:192
	global_load_dword v239, v[150:151], off offset:512
	global_load_dword v240, v[150:151], off offset:576
	global_load_dword v241, v[150:151], off offset:640
	global_load_dword v242, v[150:151], off offset:704
	s_andn2_b64 vcc, exec, s[8:9]
	s_waitcnt vmcnt(0)
	v_pk_mul_f32 v[126:127], v[126:127], v[160:161] op_sel_hi:[1,0]
	v_pk_mul_f32 v[124:125], v[124:125], v[160:161] op_sel_hi:[1,0]
	v_pk_mul_f32 v[162:163], v[122:123], v[160:161] op_sel_hi:[1,0]
	v_pk_mul_f32 v[122:123], v[120:121], v[160:161] op_sel_hi:[1,0]
	v_cvt_pk_bf16_f32 v120, v124, v125
	v_cvt_pk_bf16_f32 v121, v126, v127
	v_pk_mul_f32 v[116:117], v[116:117], v[160:161] op_sel_hi:[1,0]
	v_cvt_pk_bf16_f32 v122, v122, v123
	v_cvt_pk_bf16_f32 v123, v162, v163
	global_store_dwordx4 v[158:159], v[120:123], off
	v_pk_mul_f32 v[118:119], v[118:119], v[160:161] op_sel_hi:[1,0]
	s_nop 0
	v_pk_mul_f32 v[120:121], v[114:115], v[160:161] op_sel_hi:[1,0]
	v_pk_mul_f32 v[114:115], v[112:113], v[160:161] op_sel_hi:[1,0]
	v_cvt_pk_bf16_f32 v112, v116, v117
	v_cvt_pk_bf16_f32 v113, v118, v119
	s_nop 0
	v_cvt_pk_bf16_f32 v114, v114, v115
	v_cvt_pk_bf16_f32 v115, v120, v121
	global_store_dwordx4 v[158:159], v[112:115], off offset:256
	s_nop 1
	v_or_b32_e32 v112, 16, v144
	v_ashrrev_i32_e32 v113, 31, v112
	v_mad_i64_i32 v[114:115], s[18:19], v112, s39, v[146:147]
	v_lshl_add_u64 v[112:113], v[112:113], 2, s[88:89]
	v_lshl_add_u64 v[114:115], v[114:115], 0, v[148:149]
	s_nop 1
	v_mov_b32_e32 v112, v236
	v_pk_mul_f32 v[110:111], v[110:111], v[112:113] op_sel_hi:[1,0]
	v_pk_mul_f32 v[108:109], v[108:109], v[112:113] op_sel_hi:[1,0]
	v_pk_mul_f32 v[116:117], v[106:107], v[112:113] op_sel_hi:[1,0]
	v_pk_mul_f32 v[106:107], v[104:105], v[112:113] op_sel_hi:[1,0]
	v_cvt_pk_bf16_f32 v104, v108, v109
	v_cvt_pk_bf16_f32 v105, v110, v111
	v_pk_mul_f32 v[100:101], v[100:101], v[112:113] op_sel_hi:[1,0]
	v_cvt_pk_bf16_f32 v106, v106, v107
	v_cvt_pk_bf16_f32 v107, v116, v117
	global_store_dwordx4 v[114:115], v[104:107], off
	v_pk_mul_f32 v[102:103], v[102:103], v[112:113] op_sel_hi:[1,0]
	s_nop 0
	v_pk_mul_f32 v[104:105], v[98:99], v[112:113] op_sel_hi:[1,0]
	v_pk_mul_f32 v[98:99], v[96:97], v[112:113] op_sel_hi:[1,0]
	v_cvt_pk_bf16_f32 v96, v100, v101
	v_cvt_pk_bf16_f32 v97, v102, v103
	s_nop 0
	v_cvt_pk_bf16_f32 v98, v98, v99
	v_cvt_pk_bf16_f32 v99, v104, v105
	global_store_dwordx4 v[114:115], v[96:99], off offset:256
	s_nop 1
	v_or_b32_e32 v96, 32, v144
	v_ashrrev_i32_e32 v97, 31, v96
	v_mad_i64_i32 v[98:99], s[18:19], v96, s39, v[146:147]
	v_lshl_add_u64 v[96:97], v[96:97], 2, s[88:89]
	v_lshl_add_u64 v[98:99], v[98:99], 0, v[148:149]
	s_nop 1
	v_mov_b32_e32 v96, v237
	v_pk_mul_f32 v[94:95], v[94:95], v[96:97] op_sel_hi:[1,0]
	v_pk_mul_f32 v[92:93], v[92:93], v[96:97] op_sel_hi:[1,0]
	v_pk_mul_f32 v[100:101], v[90:91], v[96:97] op_sel_hi:[1,0]
	v_pk_mul_f32 v[90:91], v[88:89], v[96:97] op_sel_hi:[1,0]
	v_cvt_pk_bf16_f32 v88, v92, v93
	v_cvt_pk_bf16_f32 v89, v94, v95
	v_pk_mul_f32 v[84:85], v[84:85], v[96:97] op_sel_hi:[1,0]
	v_cvt_pk_bf16_f32 v90, v90, v91
	v_cvt_pk_bf16_f32 v91, v100, v101
	global_store_dwordx4 v[98:99], v[88:91], off
	v_pk_mul_f32 v[86:87], v[86:87], v[96:97] op_sel_hi:[1,0]
	s_nop 0
	v_pk_mul_f32 v[88:89], v[82:83], v[96:97] op_sel_hi:[1,0]
	v_pk_mul_f32 v[82:83], v[80:81], v[96:97] op_sel_hi:[1,0]
	v_cvt_pk_bf16_f32 v80, v84, v85
	v_cvt_pk_bf16_f32 v81, v86, v87
	s_nop 0
	v_cvt_pk_bf16_f32 v82, v82, v83
	v_cvt_pk_bf16_f32 v83, v88, v89
	global_store_dwordx4 v[98:99], v[80:83], off offset:256
	s_nop 1
	v_or_b32_e32 v80, 48, v144
	v_ashrrev_i32_e32 v81, 31, v80
	v_mad_i64_i32 v[82:83], s[18:19], v80, s39, v[146:147]
	v_lshl_add_u64 v[80:81], v[80:81], 2, s[88:89]
	v_lshl_add_u64 v[82:83], v[82:83], 0, v[148:149]
	s_nop 1
	v_mov_b32_e32 v80, v238
	v_pk_mul_f32 v[78:79], v[78:79], v[80:81] op_sel_hi:[1,0]
	v_pk_mul_f32 v[76:77], v[76:77], v[80:81] op_sel_hi:[1,0]
	v_pk_mul_f32 v[84:85], v[74:75], v[80:81] op_sel_hi:[1,0]
	v_pk_mul_f32 v[74:75], v[72:73], v[80:81] op_sel_hi:[1,0]
	v_cvt_pk_bf16_f32 v72, v76, v77
	v_cvt_pk_bf16_f32 v73, v78, v79
	v_pk_mul_f32 v[70:71], v[70:71], v[80:81] op_sel_hi:[1,0]
	v_cvt_pk_bf16_f32 v74, v74, v75
	v_cvt_pk_bf16_f32 v75, v84, v85
	global_store_dwordx4 v[82:83], v[72:75], off
	v_pk_mul_f32 v[68:69], v[68:69], v[80:81] op_sel_hi:[1,0]
	s_nop 0
	v_pk_mul_f32 v[72:73], v[66:67], v[80:81] op_sel_hi:[1,0]
	v_pk_mul_f32 v[66:67], v[64:65], v[80:81] op_sel_hi:[1,0]
	v_cvt_pk_bf16_f32 v64, v68, v69
	v_cvt_pk_bf16_f32 v65, v70, v71
	s_nop 0
	v_cvt_pk_bf16_f32 v66, v66, v67
	v_cvt_pk_bf16_f32 v67, v72, v73
	global_store_dwordx4 v[82:83], v[64:67], off offset:256
	s_nop 1
	v_mov_b32_e32 v66, v239
	v_pk_mul_f32 v[62:63], v[62:63], v[66:67] op_sel_hi:[1,0]
	v_add_u32_e32 v64, 0x80, v144
	v_mad_i64_i32 v[64:65], s[18:19], v64, s39, v[146:147]
	v_lshl_add_u64 v[64:65], v[64:65], 0, v[148:149]
	v_pk_mul_f32 v[60:61], v[60:61], v[66:67] op_sel_hi:[1,0]
	v_pk_mul_f32 v[68:69], v[58:59], v[66:67] op_sel_hi:[1,0]
	v_pk_mul_f32 v[58:59], v[56:57], v[66:67] op_sel_hi:[1,0]
	v_cvt_pk_bf16_f32 v56, v60, v61
	v_cvt_pk_bf16_f32 v57, v62, v63
	v_pk_mul_f32 v[54:55], v[54:55], v[66:67] op_sel_hi:[1,0]
	v_cvt_pk_bf16_f32 v58, v58, v59
	v_cvt_pk_bf16_f32 v59, v68, v69
	global_store_dwordx4 v[64:65], v[56:59], off
	v_pk_mul_f32 v[52:53], v[52:53], v[66:67] op_sel_hi:[1,0]
	s_nop 0
	v_pk_mul_f32 v[56:57], v[50:51], v[66:67] op_sel_hi:[1,0]
	v_pk_mul_f32 v[50:51], v[48:49], v[66:67] op_sel_hi:[1,0]
	v_cvt_pk_bf16_f32 v48, v52, v53
	v_cvt_pk_bf16_f32 v49, v54, v55
	s_nop 0
	v_cvt_pk_bf16_f32 v50, v50, v51
	v_cvt_pk_bf16_f32 v51, v56, v57
	global_store_dwordx4 v[64:65], v[48:51], off offset:256
	s_nop 1
	v_mov_b32_e32 v50, v240
	v_pk_mul_f32 v[46:47], v[46:47], v[50:51] op_sel_hi:[1,0]
	v_add_u32_e32 v48, 0x90, v144
	v_mad_i64_i32 v[48:49], s[18:19], v48, s39, v[146:147]
	v_lshl_add_u64 v[48:49], v[48:49], 0, v[148:149]
	v_pk_mul_f32 v[44:45], v[44:45], v[50:51] op_sel_hi:[1,0]
	v_pk_mul_f32 v[52:53], v[42:43], v[50:51] op_sel_hi:[1,0]
	v_pk_mul_f32 v[42:43], v[40:41], v[50:51] op_sel_hi:[1,0]
	v_cvt_pk_bf16_f32 v40, v44, v45
	v_cvt_pk_bf16_f32 v41, v46, v47
	v_pk_mul_f32 v[38:39], v[38:39], v[50:51] op_sel_hi:[1,0]
	v_cvt_pk_bf16_f32 v42, v42, v43
	v_cvt_pk_bf16_f32 v43, v52, v53
	global_store_dwordx4 v[48:49], v[40:43], off
	v_pk_mul_f32 v[36:37], v[36:37], v[50:51] op_sel_hi:[1,0]
	s_nop 0
	v_pk_mul_f32 v[40:41], v[34:35], v[50:51] op_sel_hi:[1,0]
	v_pk_mul_f32 v[34:35], v[32:33], v[50:51] op_sel_hi:[1,0]
	v_cvt_pk_bf16_f32 v32, v36, v37
	v_cvt_pk_bf16_f32 v33, v38, v39
	s_nop 0
	v_cvt_pk_bf16_f32 v34, v34, v35
	v_cvt_pk_bf16_f32 v35, v40, v41
	global_store_dwordx4 v[48:49], v[32:35], off offset:256
	s_nop 1
	v_mov_b32_e32 v34, v241
	v_pk_mul_f32 v[30:31], v[30:31], v[34:35] op_sel_hi:[1,0]
	v_add_u32_e32 v32, 0xa0, v144
	v_mad_i64_i32 v[32:33], s[18:19], v32, s39, v[146:147]
	v_lshl_add_u64 v[32:33], v[32:33], 0, v[148:149]
	v_pk_mul_f32 v[28:29], v[28:29], v[34:35] op_sel_hi:[1,0]
	v_pk_mul_f32 v[36:37], v[26:27], v[34:35] op_sel_hi:[1,0]
	v_pk_mul_f32 v[26:27], v[24:25], v[34:35] op_sel_hi:[1,0]
	v_cvt_pk_bf16_f32 v24, v28, v29
	v_cvt_pk_bf16_f32 v25, v30, v31
	v_pk_mul_f32 v[22:23], v[22:23], v[34:35] op_sel_hi:[1,0]
	v_cvt_pk_bf16_f32 v26, v26, v27
	v_cvt_pk_bf16_f32 v27, v36, v37
	global_store_dwordx4 v[32:33], v[24:27], off
	v_pk_mul_f32 v[20:21], v[20:21], v[34:35] op_sel_hi:[1,0]
	s_nop 0
	v_pk_mul_f32 v[24:25], v[18:19], v[34:35] op_sel_hi:[1,0]
	v_pk_mul_f32 v[18:19], v[16:17], v[34:35] op_sel_hi:[1,0]
	v_cvt_pk_bf16_f32 v16, v20, v21
	v_cvt_pk_bf16_f32 v17, v22, v23
	s_nop 0
	v_cvt_pk_bf16_f32 v18, v18, v19
	v_cvt_pk_bf16_f32 v19, v24, v25
	global_store_dwordx4 v[32:33], v[16:19], off offset:256
	s_nop 1
	v_mov_b32_e32 v18, v242
	v_pk_mul_f32 v[14:15], v[14:15], v[18:19] op_sel_hi:[1,0]
	v_add_u32_e32 v16, 0xb0, v144
	v_mad_i64_i32 v[16:17], s[18:19], v16, s39, v[146:147]
	v_lshl_add_u64 v[16:17], v[16:17], 0, v[148:149]
	v_pk_mul_f32 v[12:13], v[12:13], v[18:19] op_sel_hi:[1,0]
	v_pk_mul_f32 v[20:21], v[10:11], v[18:19] op_sel_hi:[1,0]
	v_pk_mul_f32 v[10:11], v[8:9], v[18:19] op_sel_hi:[1,0]
	v_cvt_pk_bf16_f32 v8, v12, v13
	v_cvt_pk_bf16_f32 v9, v14, v15
	s_mov_b64 s[18:19], -1
	v_cvt_pk_bf16_f32 v10, v10, v11
	v_cvt_pk_bf16_f32 v11, v20, v21
	global_store_dwordx4 v[16:17], v[8:11], off
	v_pk_mul_f32 v[6:7], v[6:7], v[18:19] op_sel_hi:[1,0]
	v_pk_mul_f32 v[4:5], v[4:5], v[18:19] op_sel_hi:[1,0]
	v_pk_mul_f32 v[8:9], v[2:3], v[18:19] op_sel_hi:[1,0]
	v_pk_mul_f32 v[2:3], v[0:1], v[18:19] op_sel_hi:[1,0]
	v_cvt_pk_bf16_f32 v0, v4, v5
	v_cvt_pk_bf16_f32 v1, v6, v7
	s_nop 0
	v_cvt_pk_bf16_f32 v2, v2, v3
	v_cvt_pk_bf16_f32 v3, v8, v9
	global_store_dwordx4 v[16:17], v[0:3], off offset:256
	s_cbranch_vccnz .LBB0_847
	s_andn2_b64 vcc, exec, s[0:1]
	s_cbranch_vccnz .LBB0_846
	s_barrier
	s_branch .LBB0_846

.LBB0_922:
	v_ashrrev_i32_e32 v128, 1, v140
	v_and_b32_e32 v129, -8, v128
	v_lshl_add_u32 v128, s0, 8, v141
	s_lshl_b32 s0, s4, 8
	v_readlane_b32 s1, v235, 37
	s_or_b32 s0, s1, s0
	v_add_u32_e32 v132, s0, v129
	v_ashrrev_i32_e32 v133, 31, v132
	s_movk_i32 s0, 0x1040
	v_mov_b64_e32 v[130:131], s[52:53]
	v_ashrrev_i32_e32 v129, 31, v128
	v_mad_i64_i32 v[134:135], s[4:5], v128, s0, v[130:131]
	v_lshlrev_b64 v[132:133], 1, v[132:133]
	v_lshl_add_u64 v[136:137], v[134:135], 0, v[132:133]
	v_lshl_add_u64 v[134:135], v[128:129], 2, s[88:89]
	global_load_dword v138, v[134:135], off
	global_load_dword v236, v[134:135], off offset:64
	global_load_dword v237, v[134:135], off offset:128
	global_load_dword v238, v[134:135], off offset:192
	global_load_dword v239, v[134:135], off offset:512
	global_load_dword v240, v[134:135], off offset:576
	global_load_dword v241, v[134:135], off offset:640
	global_load_dword v242, v[134:135], off offset:704
	s_waitcnt vmcnt(0)
	v_pk_mul_f32 v[126:127], v[126:127], v[138:139] op_sel_hi:[1,0]
	v_pk_mul_f32 v[124:125], v[124:125], v[138:139] op_sel_hi:[1,0]
	v_pk_mul_f32 v[140:141], v[122:123], v[138:139] op_sel_hi:[1,0]
	v_pk_mul_f32 v[122:123], v[120:121], v[138:139] op_sel_hi:[1,0]
	v_cvt_pk_bf16_f32 v120, v124, v125
	v_cvt_pk_bf16_f32 v121, v126, v127
	v_pk_mul_f32 v[116:117], v[116:117], v[138:139] op_sel_hi:[1,0]
	v_cvt_pk_bf16_f32 v122, v122, v123
	v_cvt_pk_bf16_f32 v123, v140, v141
	global_store_dwordx4 v[136:137], v[120:123], off
	v_pk_mul_f32 v[118:119], v[118:119], v[138:139] op_sel_hi:[1,0]
	s_nop 0
	v_pk_mul_f32 v[120:121], v[114:115], v[138:139] op_sel_hi:[1,0]
	v_pk_mul_f32 v[114:115], v[112:113], v[138:139] op_sel_hi:[1,0]
	v_cvt_pk_bf16_f32 v112, v116, v117
	v_cvt_pk_bf16_f32 v113, v118, v119
	s_nop 0
	v_cvt_pk_bf16_f32 v114, v114, v115
	v_cvt_pk_bf16_f32 v115, v120, v121
	global_store_dwordx4 v[136:137], v[112:115], off offset:256
	s_nop 1
	v_or_b32_e32 v112, 16, v128
	v_ashrrev_i32_e32 v113, 31, v112
	v_mad_i64_i32 v[114:115], s[4:5], v112, s0, v[130:131]
	v_lshl_add_u64 v[112:113], v[112:113], 2, s[88:89]
	v_lshl_add_u64 v[114:115], v[114:115], 0, v[132:133]
	s_nop 1
	v_mov_b32_e32 v112, v236
	v_pk_mul_f32 v[110:111], v[110:111], v[112:113] op_sel_hi:[1,0]
	v_pk_mul_f32 v[108:109], v[108:109], v[112:113] op_sel_hi:[1,0]
	v_pk_mul_f32 v[116:117], v[106:107], v[112:113] op_sel_hi:[1,0]
	v_pk_mul_f32 v[106:107], v[104:105], v[112:113] op_sel_hi:[1,0]
	v_cvt_pk_bf16_f32 v104, v108, v109
	v_cvt_pk_bf16_f32 v105, v110, v111
	v_pk_mul_f32 v[100:101], v[100:101], v[112:113] op_sel_hi:[1,0]
	v_cvt_pk_bf16_f32 v106, v106, v107
	v_cvt_pk_bf16_f32 v107, v116, v117
	global_store_dwordx4 v[114:115], v[104:107], off
	v_pk_mul_f32 v[102:103], v[102:103], v[112:113] op_sel_hi:[1,0]
	s_nop 0
	v_pk_mul_f32 v[104:105], v[98:99], v[112:113] op_sel_hi:[1,0]
	v_pk_mul_f32 v[98:99], v[96:97], v[112:113] op_sel_hi:[1,0]
	v_cvt_pk_bf16_f32 v96, v100, v101
	v_cvt_pk_bf16_f32 v97, v102, v103
	s_nop 0
	v_cvt_pk_bf16_f32 v98, v98, v99
	v_cvt_pk_bf16_f32 v99, v104, v105
	global_store_dwordx4 v[114:115], v[96:99], off offset:256
	s_nop 1
	v_or_b32_e32 v96, 32, v128
	v_ashrrev_i32_e32 v97, 31, v96
	v_mad_i64_i32 v[98:99], s[4:5], v96, s0, v[130:131]
	v_lshl_add_u64 v[96:97], v[96:97], 2, s[88:89]
	v_lshl_add_u64 v[98:99], v[98:99], 0, v[132:133]
	s_nop 1
	v_mov_b32_e32 v96, v237
	v_pk_mul_f32 v[94:95], v[94:95], v[96:97] op_sel_hi:[1,0]
	v_pk_mul_f32 v[92:93], v[92:93], v[96:97] op_sel_hi:[1,0]
	v_pk_mul_f32 v[100:101], v[90:91], v[96:97] op_sel_hi:[1,0]
	v_pk_mul_f32 v[90:91], v[88:89], v[96:97] op_sel_hi:[1,0]
	v_cvt_pk_bf16_f32 v88, v92, v93
	v_cvt_pk_bf16_f32 v89, v94, v95
	v_pk_mul_f32 v[84:85], v[84:85], v[96:97] op_sel_hi:[1,0]
	v_cvt_pk_bf16_f32 v90, v90, v91
	v_cvt_pk_bf16_f32 v91, v100, v101
	global_store_dwordx4 v[98:99], v[88:91], off
	v_pk_mul_f32 v[86:87], v[86:87], v[96:97] op_sel_hi:[1,0]
	s_nop 0
	v_pk_mul_f32 v[88:89], v[82:83], v[96:97] op_sel_hi:[1,0]
	v_pk_mul_f32 v[82:83], v[80:81], v[96:97] op_sel_hi:[1,0]
	v_cvt_pk_bf16_f32 v80, v84, v85
	v_cvt_pk_bf16_f32 v81, v86, v87
	s_nop 0
	v_cvt_pk_bf16_f32 v82, v82, v83
	v_cvt_pk_bf16_f32 v83, v88, v89
	global_store_dwordx4 v[98:99], v[80:83], off offset:256
	s_nop 1
	v_or_b32_e32 v80, 48, v128
	v_ashrrev_i32_e32 v81, 31, v80
	v_mad_i64_i32 v[82:83], s[4:5], v80, s0, v[130:131]
	v_lshl_add_u64 v[80:81], v[80:81], 2, s[88:89]
	v_lshl_add_u64 v[82:83], v[82:83], 0, v[132:133]
	s_nop 1
	v_mov_b32_e32 v80, v238
	v_pk_mul_f32 v[78:79], v[78:79], v[80:81] op_sel_hi:[1,0]
	v_pk_mul_f32 v[76:77], v[76:77], v[80:81] op_sel_hi:[1,0]
	v_pk_mul_f32 v[84:85], v[74:75], v[80:81] op_sel_hi:[1,0]
	v_pk_mul_f32 v[74:75], v[72:73], v[80:81] op_sel_hi:[1,0]
	v_cvt_pk_bf16_f32 v72, v76, v77
	v_cvt_pk_bf16_f32 v73, v78, v79
	v_pk_mul_f32 v[70:71], v[70:71], v[80:81] op_sel_hi:[1,0]
	v_cvt_pk_bf16_f32 v74, v74, v75
	v_cvt_pk_bf16_f32 v75, v84, v85
	global_store_dwordx4 v[82:83], v[72:75], off
	v_pk_mul_f32 v[68:69], v[68:69], v[80:81] op_sel_hi:[1,0]
	s_nop 0
	v_pk_mul_f32 v[72:73], v[66:67], v[80:81] op_sel_hi:[1,0]
	v_pk_mul_f32 v[66:67], v[64:65], v[80:81] op_sel_hi:[1,0]
	v_cvt_pk_bf16_f32 v64, v68, v69
	v_cvt_pk_bf16_f32 v65, v70, v71
	s_nop 0
	v_cvt_pk_bf16_f32 v66, v66, v67
	v_cvt_pk_bf16_f32 v67, v72, v73
	global_store_dwordx4 v[82:83], v[64:67], off offset:256
	s_nop 1
	v_mov_b32_e32 v66, v239
	v_pk_mul_f32 v[62:63], v[62:63], v[66:67] op_sel_hi:[1,0]
	v_add_u32_e32 v64, 0x80, v128
	v_mad_i64_i32 v[64:65], s[4:5], v64, s0, v[130:131]
	v_lshl_add_u64 v[64:65], v[64:65], 0, v[132:133]
	v_pk_mul_f32 v[60:61], v[60:61], v[66:67] op_sel_hi:[1,0]
	v_pk_mul_f32 v[68:69], v[58:59], v[66:67] op_sel_hi:[1,0]
	v_pk_mul_f32 v[58:59], v[56:57], v[66:67] op_sel_hi:[1,0]
	v_cvt_pk_bf16_f32 v56, v60, v61
	v_cvt_pk_bf16_f32 v57, v62, v63
	v_pk_mul_f32 v[54:55], v[54:55], v[66:67] op_sel_hi:[1,0]
	v_cvt_pk_bf16_f32 v58, v58, v59
	v_cvt_pk_bf16_f32 v59, v68, v69
	global_store_dwordx4 v[64:65], v[56:59], off
	v_pk_mul_f32 v[52:53], v[52:53], v[66:67] op_sel_hi:[1,0]
	s_nop 0
	v_pk_mul_f32 v[56:57], v[50:51], v[66:67] op_sel_hi:[1,0]
	v_pk_mul_f32 v[50:51], v[48:49], v[66:67] op_sel_hi:[1,0]
	v_cvt_pk_bf16_f32 v48, v52, v53
	v_cvt_pk_bf16_f32 v49, v54, v55
	s_nop 0
	v_cvt_pk_bf16_f32 v50, v50, v51
	v_cvt_pk_bf16_f32 v51, v56, v57
	global_store_dwordx4 v[64:65], v[48:51], off offset:256
	s_nop 1
	v_mov_b32_e32 v50, v240
	v_pk_mul_f32 v[46:47], v[46:47], v[50:51] op_sel_hi:[1,0]
	v_add_u32_e32 v48, 0x90, v128
	v_mad_i64_i32 v[48:49], s[4:5], v48, s0, v[130:131]
	v_lshl_add_u64 v[48:49], v[48:49], 0, v[132:133]
	v_pk_mul_f32 v[44:45], v[44:45], v[50:51] op_sel_hi:[1,0]
	v_pk_mul_f32 v[52:53], v[42:43], v[50:51] op_sel_hi:[1,0]
	v_pk_mul_f32 v[42:43], v[40:41], v[50:51] op_sel_hi:[1,0]
	v_cvt_pk_bf16_f32 v40, v44, v45
	v_cvt_pk_bf16_f32 v41, v46, v47
	v_pk_mul_f32 v[38:39], v[38:39], v[50:51] op_sel_hi:[1,0]
	v_cvt_pk_bf16_f32 v42, v42, v43
	v_cvt_pk_bf16_f32 v43, v52, v53
	global_store_dwordx4 v[48:49], v[40:43], off
	v_pk_mul_f32 v[36:37], v[36:37], v[50:51] op_sel_hi:[1,0]
	s_nop 0
	v_pk_mul_f32 v[40:41], v[34:35], v[50:51] op_sel_hi:[1,0]
	v_pk_mul_f32 v[34:35], v[32:33], v[50:51] op_sel_hi:[1,0]
	v_cvt_pk_bf16_f32 v32, v36, v37
	v_cvt_pk_bf16_f32 v33, v38, v39
	s_nop 0
	v_cvt_pk_bf16_f32 v34, v34, v35
	v_cvt_pk_bf16_f32 v35, v40, v41
	global_store_dwordx4 v[48:49], v[32:35], off offset:256
	s_nop 1
	v_mov_b32_e32 v34, v241
	v_pk_mul_f32 v[30:31], v[30:31], v[34:35] op_sel_hi:[1,0]
	v_add_u32_e32 v32, 0xa0, v128
	v_mad_i64_i32 v[32:33], s[4:5], v32, s0, v[130:131]
	v_lshl_add_u64 v[32:33], v[32:33], 0, v[132:133]
	v_pk_mul_f32 v[28:29], v[28:29], v[34:35] op_sel_hi:[1,0]
	v_pk_mul_f32 v[36:37], v[26:27], v[34:35] op_sel_hi:[1,0]
	v_pk_mul_f32 v[26:27], v[24:25], v[34:35] op_sel_hi:[1,0]
	v_cvt_pk_bf16_f32 v24, v28, v29
	v_cvt_pk_bf16_f32 v25, v30, v31
	v_pk_mul_f32 v[22:23], v[22:23], v[34:35] op_sel_hi:[1,0]
	v_cvt_pk_bf16_f32 v26, v26, v27
	v_cvt_pk_bf16_f32 v27, v36, v37
	global_store_dwordx4 v[32:33], v[24:27], off
	v_pk_mul_f32 v[20:21], v[20:21], v[34:35] op_sel_hi:[1,0]
	s_nop 0
	v_pk_mul_f32 v[24:25], v[18:19], v[34:35] op_sel_hi:[1,0]
	v_pk_mul_f32 v[18:19], v[16:17], v[34:35] op_sel_hi:[1,0]
	v_cvt_pk_bf16_f32 v16, v20, v21
	v_cvt_pk_bf16_f32 v17, v22, v23
	s_nop 0
	v_cvt_pk_bf16_f32 v18, v18, v19
	v_cvt_pk_bf16_f32 v19, v24, v25
	global_store_dwordx4 v[32:33], v[16:19], off offset:256
	s_nop 1
	v_mov_b32_e32 v18, v242
	v_pk_mul_f32 v[14:15], v[14:15], v[18:19] op_sel_hi:[1,0]
	v_add_u32_e32 v16, 0xb0, v128
	v_mad_i64_i32 v[16:17], s[0:1], v16, s0, v[130:131]
	v_lshl_add_u64 v[16:17], v[16:17], 0, v[132:133]
	v_pk_mul_f32 v[12:13], v[12:13], v[18:19] op_sel_hi:[1,0]
	v_pk_mul_f32 v[20:21], v[10:11], v[18:19] op_sel_hi:[1,0]
	v_pk_mul_f32 v[10:11], v[8:9], v[18:19] op_sel_hi:[1,0]
	v_cvt_pk_bf16_f32 v8, v12, v13
	v_cvt_pk_bf16_f32 v9, v14, v15
	v_pk_mul_f32 v[6:7], v[6:7], v[18:19] op_sel_hi:[1,0]
	v_cvt_pk_bf16_f32 v10, v10, v11
	v_cvt_pk_bf16_f32 v11, v20, v21
	global_store_dwordx4 v[16:17], v[8:11], off
	v_pk_mul_f32 v[4:5], v[4:5], v[18:19] op_sel_hi:[1,0]
	v_readlane_b32 s0, v235, 41
	v_pk_mul_f32 v[8:9], v[2:3], v[18:19] op_sel_hi:[1,0]
	v_pk_mul_f32 v[2:3], v[0:1], v[18:19] op_sel_hi:[1,0]
	v_cvt_pk_bf16_f32 v0, v4, v5
	v_cvt_pk_bf16_f32 v1, v6, v7
	v_readlane_b32 s1, v235, 42
	v_cvt_pk_bf16_f32 v2, v2, v3
	v_cvt_pk_bf16_f32 v3, v8, v9
	global_store_dwordx4 v[16:17], v[0:3], off offset:256
	s_waitcnt vmcnt(0)
	s_barrier
	s_waitcnt vmcnt(0)
	s_and_b64 vcc, exec, s[0:1]
	s_barrier
	s_cbranch_vccnz .LBB0_936
	v_mbcnt_lo_u32_b32 v0, -1, 0
	v_mbcnt_hi_u32_b32 v0, -1, v0
	s_nop 0
	v_cmp_eq_u32_e32 vcc, 0, v0
	s_and_saveexec_b64 s[0:1], vcc
	s_cbranch_execz .LBB0_935
	s_mov_b64 s[6:7], exec
	buffer_wbl2 sc1
	s_waitcnt vmcnt(0)
	s_waitcnt vmcnt(0)
	v_mbcnt_lo_u32_b32 v0, s6, 0
	s_add_u32 s4, s78, 0x3800
	v_mbcnt_hi_u32_b32 v0, s7, v0
	s_addc_u32 s5, s79, 0
	v_cmp_eq_u32_e32 vcc, 0, v0
	s_and_saveexec_b64 s[8:9], vcc
	s_cbranch_execz .LBB0_926
	s_bcnt1_i32_b64 s6, s[6:7]
	v_mov_b32_e32 v0, 0
	v_mov_b32_e32 v1, s6
	global_atomic_add v0, v1, s[4:5]

.LBB0_1565:
	v_lshl_add_u32 v148, s19, 8, v154
	v_lshl_add_u32 v144, s18, 8, v152
	v_ashrrev_i32_e32 v149, 31, v148
	v_mov_b64_e32 v[146:147], s[52:53]
	v_ashrrev_i32_e32 v145, 31, v144
	v_mad_i64_i32 v[150:151], s[18:19], v144, s39, v[146:147]
	v_lshlrev_b64 v[148:149], 1, v[148:149]
	v_lshl_add_u64 v[158:159], v[150:151], 0, v[148:149]
	v_lshl_add_u64 v[150:151], v[144:145], 2, s[88:89]
	global_load_dword v160, v[150:151], off
	global_load_dword v236, v[150:151], off offset:64
	global_load_dword v237, v[150:151], off offset:128
	global_load_dword v238, v[150:151], off offset:192
	global_load_dword v239, v[150:151], off offset:512
	global_load_dword v240, v[150:151], off offset:576
	global_load_dword v241, v[150:151], off offset:640
	global_load_dword v242, v[150:151], off offset:704
	s_andn2_b64 vcc, exec, s[16:17]
	s_waitcnt vmcnt(0)
	v_pk_mul_f32 v[126:127], v[126:127], v[160:161] op_sel_hi:[1,0]
	v_pk_mul_f32 v[124:125], v[124:125], v[160:161] op_sel_hi:[1,0]
	v_pk_mul_f32 v[162:163], v[122:123], v[160:161] op_sel_hi:[1,0]
	v_pk_mul_f32 v[122:123], v[120:121], v[160:161] op_sel_hi:[1,0]
	v_cvt_pk_bf16_f32 v120, v124, v125
	v_cvt_pk_bf16_f32 v121, v126, v127
	v_pk_mul_f32 v[116:117], v[116:117], v[160:161] op_sel_hi:[1,0]
	v_cvt_pk_bf16_f32 v122, v122, v123
	v_cvt_pk_bf16_f32 v123, v162, v163
	global_store_dwordx4 v[158:159], v[120:123], off
	v_pk_mul_f32 v[118:119], v[118:119], v[160:161] op_sel_hi:[1,0]
	s_nop 0
	v_pk_mul_f32 v[120:121], v[114:115], v[160:161] op_sel_hi:[1,0]
	v_pk_mul_f32 v[114:115], v[112:113], v[160:161] op_sel_hi:[1,0]
	v_cvt_pk_bf16_f32 v112, v116, v117
	v_cvt_pk_bf16_f32 v113, v118, v119
	s_nop 0
	v_cvt_pk_bf16_f32 v114, v114, v115
	v_cvt_pk_bf16_f32 v115, v120, v121
	global_store_dwordx4 v[158:159], v[112:115], off offset:256
	s_nop 1
	v_or_b32_e32 v112, 16, v144
	v_ashrrev_i32_e32 v113, 31, v112
	v_mad_i64_i32 v[114:115], s[18:19], v112, s39, v[146:147]
	v_lshl_add_u64 v[112:113], v[112:113], 2, s[88:89]
	v_lshl_add_u64 v[114:115], v[114:115], 0, v[148:149]
	s_nop 1
	v_mov_b32_e32 v112, v236
	v_pk_mul_f32 v[110:111], v[110:111], v[112:113] op_sel_hi:[1,0]
	v_pk_mul_f32 v[108:109], v[108:109], v[112:113] op_sel_hi:[1,0]
	v_pk_mul_f32 v[116:117], v[106:107], v[112:113] op_sel_hi:[1,0]
	v_pk_mul_f32 v[106:107], v[104:105], v[112:113] op_sel_hi:[1,0]
	v_cvt_pk_bf16_f32 v104, v108, v109
	v_cvt_pk_bf16_f32 v105, v110, v111
	v_pk_mul_f32 v[100:101], v[100:101], v[112:113] op_sel_hi:[1,0]
	v_cvt_pk_bf16_f32 v106, v106, v107
	v_cvt_pk_bf16_f32 v107, v116, v117
	global_store_dwordx4 v[114:115], v[104:107], off
	v_pk_mul_f32 v[102:103], v[102:103], v[112:113] op_sel_hi:[1,0]
	s_nop 0
	v_pk_mul_f32 v[104:105], v[98:99], v[112:113] op_sel_hi:[1,0]
	v_pk_mul_f32 v[98:99], v[96:97], v[112:113] op_sel_hi:[1,0]
	v_cvt_pk_bf16_f32 v96, v100, v101
	v_cvt_pk_bf16_f32 v97, v102, v103
	s_nop 0
	v_cvt_pk_bf16_f32 v98, v98, v99
	v_cvt_pk_bf16_f32 v99, v104, v105
	global_store_dwordx4 v[114:115], v[96:99], off offset:256
	s_nop 1
	v_or_b32_e32 v96, 32, v144
	v_ashrrev_i32_e32 v97, 31, v96
	v_mad_i64_i32 v[98:99], s[18:19], v96, s39, v[146:147]
	v_lshl_add_u64 v[96:97], v[96:97], 2, s[88:89]
	v_lshl_add_u64 v[98:99], v[98:99], 0, v[148:149]
	s_nop 1
	v_mov_b32_e32 v96, v237
	v_pk_mul_f32 v[94:95], v[94:95], v[96:97] op_sel_hi:[1,0]
	v_pk_mul_f32 v[92:93], v[92:93], v[96:97] op_sel_hi:[1,0]
	v_pk_mul_f32 v[100:101], v[90:91], v[96:97] op_sel_hi:[1,0]
	v_pk_mul_f32 v[90:91], v[88:89], v[96:97] op_sel_hi:[1,0]
	v_cvt_pk_bf16_f32 v88, v92, v93
	v_cvt_pk_bf16_f32 v89, v94, v95
	v_pk_mul_f32 v[84:85], v[84:85], v[96:97] op_sel_hi:[1,0]
	v_cvt_pk_bf16_f32 v90, v90, v91
	v_cvt_pk_bf16_f32 v91, v100, v101
	global_store_dwordx4 v[98:99], v[88:91], off
	v_pk_mul_f32 v[86:87], v[86:87], v[96:97] op_sel_hi:[1,0]
	s_nop 0
	v_pk_mul_f32 v[88:89], v[82:83], v[96:97] op_sel_hi:[1,0]
	v_pk_mul_f32 v[82:83], v[80:81], v[96:97] op_sel_hi:[1,0]
	v_cvt_pk_bf16_f32 v80, v84, v85
	v_cvt_pk_bf16_f32 v81, v86, v87
	s_nop 0
	v_cvt_pk_bf16_f32 v82, v82, v83
	v_cvt_pk_bf16_f32 v83, v88, v89
	global_store_dwordx4 v[98:99], v[80:83], off offset:256
	s_nop 1
	v_or_b32_e32 v80, 48, v144
	v_ashrrev_i32_e32 v81, 31, v80
	v_mad_i64_i32 v[82:83], s[18:19], v80, s39, v[146:147]
	v_lshl_add_u64 v[80:81], v[80:81], 2, s[88:89]
	v_lshl_add_u64 v[82:83], v[82:83], 0, v[148:149]
	s_nop 1
	v_mov_b32_e32 v80, v238
	v_pk_mul_f32 v[78:79], v[78:79], v[80:81] op_sel_hi:[1,0]
	v_pk_mul_f32 v[76:77], v[76:77], v[80:81] op_sel_hi:[1,0]
	v_pk_mul_f32 v[84:85], v[74:75], v[80:81] op_sel_hi:[1,0]
	v_pk_mul_f32 v[74:75], v[72:73], v[80:81] op_sel_hi:[1,0]
	v_cvt_pk_bf16_f32 v72, v76, v77
	v_cvt_pk_bf16_f32 v73, v78, v79
	v_pk_mul_f32 v[70:71], v[70:71], v[80:81] op_sel_hi:[1,0]
	v_cvt_pk_bf16_f32 v74, v74, v75
	v_cvt_pk_bf16_f32 v75, v84, v85
	global_store_dwordx4 v[82:83], v[72:75], off
	v_pk_mul_f32 v[68:69], v[68:69], v[80:81] op_sel_hi:[1,0]
	s_nop 0
	v_pk_mul_f32 v[72:73], v[66:67], v[80:81] op_sel_hi:[1,0]
	v_pk_mul_f32 v[66:67], v[64:65], v[80:81] op_sel_hi:[1,0]
	v_cvt_pk_bf16_f32 v64, v68, v69
	v_cvt_pk_bf16_f32 v65, v70, v71
	s_nop 0
	v_cvt_pk_bf16_f32 v66, v66, v67
	v_cvt_pk_bf16_f32 v67, v72, v73
	global_store_dwordx4 v[82:83], v[64:67], off offset:256
	s_nop 1
	v_mov_b32_e32 v66, v239
	v_pk_mul_f32 v[62:63], v[62:63], v[66:67] op_sel_hi:[1,0]
	v_add_u32_e32 v64, 0x80, v144
	v_mad_i64_i32 v[64:65], s[18:19], v64, s39, v[146:147]
	v_lshl_add_u64 v[64:65], v[64:65], 0, v[148:149]
	v_pk_mul_f32 v[60:61], v[60:61], v[66:67] op_sel_hi:[1,0]
	v_pk_mul_f32 v[68:69], v[58:59], v[66:67] op_sel_hi:[1,0]
	v_pk_mul_f32 v[58:59], v[56:57], v[66:67] op_sel_hi:[1,0]
	v_cvt_pk_bf16_f32 v56, v60, v61
	v_cvt_pk_bf16_f32 v57, v62, v63
	v_pk_mul_f32 v[54:55], v[54:55], v[66:67] op_sel_hi:[1,0]
	v_cvt_pk_bf16_f32 v58, v58, v59
	v_cvt_pk_bf16_f32 v59, v68, v69
	global_store_dwordx4 v[64:65], v[56:59], off
	v_pk_mul_f32 v[52:53], v[52:53], v[66:67] op_sel_hi:[1,0]
	s_nop 0
	v_pk_mul_f32 v[56:57], v[50:51], v[66:67] op_sel_hi:[1,0]
	v_pk_mul_f32 v[50:51], v[48:49], v[66:67] op_sel_hi:[1,0]
	v_cvt_pk_bf16_f32 v48, v52, v53
	v_cvt_pk_bf16_f32 v49, v54, v55
	s_nop 0
	v_cvt_pk_bf16_f32 v50, v50, v51
	v_cvt_pk_bf16_f32 v51, v56, v57
	global_store_dwordx4 v[64:65], v[48:51], off offset:256
	s_nop 1
	v_mov_b32_e32 v50, v240
	v_pk_mul_f32 v[46:47], v[46:47], v[50:51] op_sel_hi:[1,0]
	v_add_u32_e32 v48, 0x90, v144
	v_mad_i64_i32 v[48:49], s[18:19], v48, s39, v[146:147]
	v_lshl_add_u64 v[48:49], v[48:49], 0, v[148:149]
	v_pk_mul_f32 v[44:45], v[44:45], v[50:51] op_sel_hi:[1,0]
	v_pk_mul_f32 v[52:53], v[42:43], v[50:51] op_sel_hi:[1,0]
	v_pk_mul_f32 v[42:43], v[40:41], v[50:51] op_sel_hi:[1,0]
	v_cvt_pk_bf16_f32 v40, v44, v45
	v_cvt_pk_bf16_f32 v41, v46, v47
	v_pk_mul_f32 v[38:39], v[38:39], v[50:51] op_sel_hi:[1,0]
	v_cvt_pk_bf16_f32 v42, v42, v43
	v_cvt_pk_bf16_f32 v43, v52, v53
	global_store_dwordx4 v[48:49], v[40:43], off
	v_pk_mul_f32 v[36:37], v[36:37], v[50:51] op_sel_hi:[1,0]
	s_nop 0
	v_pk_mul_f32 v[40:41], v[34:35], v[50:51] op_sel_hi:[1,0]
	v_pk_mul_f32 v[34:35], v[32:33], v[50:51] op_sel_hi:[1,0]
	v_cvt_pk_bf16_f32 v32, v36, v37
	v_cvt_pk_bf16_f32 v33, v38, v39
	s_nop 0
	v_cvt_pk_bf16_f32 v34, v34, v35
	v_cvt_pk_bf16_f32 v35, v40, v41
	global_store_dwordx4 v[48:49], v[32:35], off offset:256
	s_nop 1
	v_mov_b32_e32 v34, v241
	v_pk_mul_f32 v[30:31], v[30:31], v[34:35] op_sel_hi:[1,0]
	v_add_u32_e32 v32, 0xa0, v144
	v_mad_i64_i32 v[32:33], s[18:19], v32, s39, v[146:147]
	v_lshl_add_u64 v[32:33], v[32:33], 0, v[148:149]
	v_pk_mul_f32 v[28:29], v[28:29], v[34:35] op_sel_hi:[1,0]
	v_pk_mul_f32 v[36:37], v[26:27], v[34:35] op_sel_hi:[1,0]
	v_pk_mul_f32 v[26:27], v[24:25], v[34:35] op_sel_hi:[1,0]
	v_cvt_pk_bf16_f32 v24, v28, v29
	v_cvt_pk_bf16_f32 v25, v30, v31
	v_pk_mul_f32 v[22:23], v[22:23], v[34:35] op_sel_hi:[1,0]
	v_cvt_pk_bf16_f32 v26, v26, v27
	v_cvt_pk_bf16_f32 v27, v36, v37
	global_store_dwordx4 v[32:33], v[24:27], off
	v_pk_mul_f32 v[20:21], v[20:21], v[34:35] op_sel_hi:[1,0]
	s_nop 0
	v_pk_mul_f32 v[24:25], v[18:19], v[34:35] op_sel_hi:[1,0]
	v_pk_mul_f32 v[18:19], v[16:17], v[34:35] op_sel_hi:[1,0]
	v_cvt_pk_bf16_f32 v16, v20, v21
	v_cvt_pk_bf16_f32 v17, v22, v23
	s_nop 0
	v_cvt_pk_bf16_f32 v18, v18, v19
	v_cvt_pk_bf16_f32 v19, v24, v25
	global_store_dwordx4 v[32:33], v[16:19], off offset:256
	s_nop 1
	v_mov_b32_e32 v18, v242
	v_pk_mul_f32 v[14:15], v[14:15], v[18:19] op_sel_hi:[1,0]
	v_add_u32_e32 v16, 0xb0, v144
	v_mad_i64_i32 v[16:17], s[18:19], v16, s39, v[146:147]
	v_lshl_add_u64 v[16:17], v[16:17], 0, v[148:149]
	v_pk_mul_f32 v[12:13], v[12:13], v[18:19] op_sel_hi:[1,0]
	v_pk_mul_f32 v[20:21], v[10:11], v[18:19] op_sel_hi:[1,0]
	v_pk_mul_f32 v[10:11], v[8:9], v[18:19] op_sel_hi:[1,0]
	v_cvt_pk_bf16_f32 v8, v12, v13
	v_cvt_pk_bf16_f32 v9, v14, v15
	s_mov_b64 s[18:19], -1
	v_cvt_pk_bf16_f32 v10, v10, v11
	v_cvt_pk_bf16_f32 v11, v20, v21
	global_store_dwordx4 v[16:17], v[8:11], off
	v_pk_mul_f32 v[6:7], v[6:7], v[18:19] op_sel_hi:[1,0]
	v_pk_mul_f32 v[4:5], v[4:5], v[18:19] op_sel_hi:[1,0]
	v_pk_mul_f32 v[8:9], v[2:3], v[18:19] op_sel_hi:[1,0]
	v_pk_mul_f32 v[2:3], v[0:1], v[18:19] op_sel_hi:[1,0]
	v_cvt_pk_bf16_f32 v0, v4, v5
	v_cvt_pk_bf16_f32 v1, v6, v7
	s_nop 0
	v_cvt_pk_bf16_f32 v2, v2, v3
	v_cvt_pk_bf16_f32 v3, v8, v9
	global_store_dwordx4 v[16:17], v[0:3], off offset:256
	s_cbranch_vccnz .LBB0_1556
	s_andn2_b64 vcc, exec, s[0:1]
	s_cbranch_vccnz .LBB0_1555
	s_barrier
	s_branch .LBB0_1555

.LBB0_1631:
	v_ashrrev_i32_e32 v128, 1, v140
	v_and_b32_e32 v129, -8, v128
	v_lshl_add_u32 v128, s0, 8, v141
	s_lshl_b32 s0, s4, 8
	v_readlane_b32 s1, v235, 37
	s_or_b32 s0, s1, s0
	v_add_u32_e32 v132, s0, v129
	v_ashrrev_i32_e32 v133, 31, v132
	s_movk_i32 s0, 0x1040
	v_mov_b64_e32 v[130:131], s[52:53]
	v_ashrrev_i32_e32 v129, 31, v128
	v_mad_i64_i32 v[134:135], s[4:5], v128, s0, v[130:131]
	v_lshlrev_b64 v[132:133], 1, v[132:133]
	v_lshl_add_u64 v[136:137], v[134:135], 0, v[132:133]
	v_lshl_add_u64 v[134:135], v[128:129], 2, s[88:89]
	global_load_dword v138, v[134:135], off
	global_load_dword v236, v[134:135], off offset:64
	global_load_dword v237, v[134:135], off offset:128
	global_load_dword v238, v[134:135], off offset:192
	global_load_dword v239, v[134:135], off offset:512
	global_load_dword v240, v[134:135], off offset:576
	global_load_dword v241, v[134:135], off offset:640
	global_load_dword v242, v[134:135], off offset:704
	s_waitcnt vmcnt(0)
	v_pk_mul_f32 v[126:127], v[126:127], v[138:139] op_sel_hi:[1,0]
	v_pk_mul_f32 v[124:125], v[124:125], v[138:139] op_sel_hi:[1,0]
	v_pk_mul_f32 v[140:141], v[122:123], v[138:139] op_sel_hi:[1,0]
	v_pk_mul_f32 v[122:123], v[120:121], v[138:139] op_sel_hi:[1,0]
	v_cvt_pk_bf16_f32 v120, v124, v125
	v_cvt_pk_bf16_f32 v121, v126, v127
	v_pk_mul_f32 v[116:117], v[116:117], v[138:139] op_sel_hi:[1,0]
	v_cvt_pk_bf16_f32 v122, v122, v123
	v_cvt_pk_bf16_f32 v123, v140, v141
	global_store_dwordx4 v[136:137], v[120:123], off
	v_pk_mul_f32 v[118:119], v[118:119], v[138:139] op_sel_hi:[1,0]
	s_nop 0
	v_pk_mul_f32 v[120:121], v[114:115], v[138:139] op_sel_hi:[1,0]
	v_pk_mul_f32 v[114:115], v[112:113], v[138:139] op_sel_hi:[1,0]
	v_cvt_pk_bf16_f32 v112, v116, v117
	v_cvt_pk_bf16_f32 v113, v118, v119
	s_nop 0
	v_cvt_pk_bf16_f32 v114, v114, v115
	v_cvt_pk_bf16_f32 v115, v120, v121
	global_store_dwordx4 v[136:137], v[112:115], off offset:256
	s_nop 1
	v_or_b32_e32 v112, 16, v128
	v_ashrrev_i32_e32 v113, 31, v112
	v_mad_i64_i32 v[114:115], s[4:5], v112, s0, v[130:131]
	v_lshl_add_u64 v[112:113], v[112:113], 2, s[88:89]
	v_lshl_add_u64 v[114:115], v[114:115], 0, v[132:133]
	s_nop 1
	v_mov_b32_e32 v112, v236
	v_pk_mul_f32 v[110:111], v[110:111], v[112:113] op_sel_hi:[1,0]
	v_pk_mul_f32 v[108:109], v[108:109], v[112:113] op_sel_hi:[1,0]
	v_pk_mul_f32 v[116:117], v[106:107], v[112:113] op_sel_hi:[1,0]
	v_pk_mul_f32 v[106:107], v[104:105], v[112:113] op_sel_hi:[1,0]
	v_cvt_pk_bf16_f32 v104, v108, v109
	v_cvt_pk_bf16_f32 v105, v110, v111
	v_pk_mul_f32 v[100:101], v[100:101], v[112:113] op_sel_hi:[1,0]
	v_cvt_pk_bf16_f32 v106, v106, v107
	v_cvt_pk_bf16_f32 v107, v116, v117
	global_store_dwordx4 v[114:115], v[104:107], off
	v_pk_mul_f32 v[102:103], v[102:103], v[112:113] op_sel_hi:[1,0]
	s_nop 0
	v_pk_mul_f32 v[104:105], v[98:99], v[112:113] op_sel_hi:[1,0]
	v_pk_mul_f32 v[98:99], v[96:97], v[112:113] op_sel_hi:[1,0]
	v_cvt_pk_bf16_f32 v96, v100, v101
	v_cvt_pk_bf16_f32 v97, v102, v103
	s_nop 0
	v_cvt_pk_bf16_f32 v98, v98, v99
	v_cvt_pk_bf16_f32 v99, v104, v105
	global_store_dwordx4 v[114:115], v[96:99], off offset:256
	s_nop 1
	v_or_b32_e32 v96, 32, v128
	v_ashrrev_i32_e32 v97, 31, v96
	v_mad_i64_i32 v[98:99], s[4:5], v96, s0, v[130:131]
	v_lshl_add_u64 v[96:97], v[96:97], 2, s[88:89]
	v_lshl_add_u64 v[98:99], v[98:99], 0, v[132:133]
	s_nop 1
	v_mov_b32_e32 v96, v237
	v_pk_mul_f32 v[94:95], v[94:95], v[96:97] op_sel_hi:[1,0]
	v_pk_mul_f32 v[92:93], v[92:93], v[96:97] op_sel_hi:[1,0]
	v_pk_mul_f32 v[100:101], v[90:91], v[96:97] op_sel_hi:[1,0]
	v_pk_mul_f32 v[90:91], v[88:89], v[96:97] op_sel_hi:[1,0]
	v_cvt_pk_bf16_f32 v88, v92, v93
	v_cvt_pk_bf16_f32 v89, v94, v95
	v_pk_mul_f32 v[84:85], v[84:85], v[96:97] op_sel_hi:[1,0]
	v_cvt_pk_bf16_f32 v90, v90, v91
	v_cvt_pk_bf16_f32 v91, v100, v101
	global_store_dwordx4 v[98:99], v[88:91], off
	v_pk_mul_f32 v[86:87], v[86:87], v[96:97] op_sel_hi:[1,0]
	s_nop 0
	v_pk_mul_f32 v[88:89], v[82:83], v[96:97] op_sel_hi:[1,0]
	v_pk_mul_f32 v[82:83], v[80:81], v[96:97] op_sel_hi:[1,0]
	v_cvt_pk_bf16_f32 v80, v84, v85
	v_cvt_pk_bf16_f32 v81, v86, v87
	s_nop 0
	v_cvt_pk_bf16_f32 v82, v82, v83
	v_cvt_pk_bf16_f32 v83, v88, v89
	global_store_dwordx4 v[98:99], v[80:83], off offset:256
	s_nop 1
	v_or_b32_e32 v80, 48, v128
	v_ashrrev_i32_e32 v81, 31, v80
	v_mad_i64_i32 v[82:83], s[4:5], v80, s0, v[130:131]
	v_lshl_add_u64 v[80:81], v[80:81], 2, s[88:89]
	v_lshl_add_u64 v[82:83], v[82:83], 0, v[132:133]
	s_nop 1
	v_mov_b32_e32 v80, v238
	v_pk_mul_f32 v[78:79], v[78:79], v[80:81] op_sel_hi:[1,0]
	v_pk_mul_f32 v[76:77], v[76:77], v[80:81] op_sel_hi:[1,0]
	v_pk_mul_f32 v[84:85], v[74:75], v[80:81] op_sel_hi:[1,0]
	v_pk_mul_f32 v[74:75], v[72:73], v[80:81] op_sel_hi:[1,0]
	v_cvt_pk_bf16_f32 v72, v76, v77
	v_cvt_pk_bf16_f32 v73, v78, v79
	v_pk_mul_f32 v[70:71], v[70:71], v[80:81] op_sel_hi:[1,0]
	v_cvt_pk_bf16_f32 v74, v74, v75
	v_cvt_pk_bf16_f32 v75, v84, v85
	global_store_dwordx4 v[82:83], v[72:75], off
	v_pk_mul_f32 v[68:69], v[68:69], v[80:81] op_sel_hi:[1,0]
	s_nop 0
	v_pk_mul_f32 v[72:73], v[66:67], v[80:81] op_sel_hi:[1,0]
	v_pk_mul_f32 v[66:67], v[64:65], v[80:81] op_sel_hi:[1,0]
	v_cvt_pk_bf16_f32 v64, v68, v69
	v_cvt_pk_bf16_f32 v65, v70, v71
	s_nop 0
	v_cvt_pk_bf16_f32 v66, v66, v67
	v_cvt_pk_bf16_f32 v67, v72, v73
	global_store_dwordx4 v[82:83], v[64:67], off offset:256
	s_nop 1
	v_mov_b32_e32 v66, v239
	v_pk_mul_f32 v[62:63], v[62:63], v[66:67] op_sel_hi:[1,0]
	v_add_u32_e32 v64, 0x80, v128
	v_mad_i64_i32 v[64:65], s[4:5], v64, s0, v[130:131]
	v_lshl_add_u64 v[64:65], v[64:65], 0, v[132:133]
	v_pk_mul_f32 v[60:61], v[60:61], v[66:67] op_sel_hi:[1,0]
	v_pk_mul_f32 v[68:69], v[58:59], v[66:67] op_sel_hi:[1,0]
	v_pk_mul_f32 v[58:59], v[56:57], v[66:67] op_sel_hi:[1,0]
	v_cvt_pk_bf16_f32 v56, v60, v61
	v_cvt_pk_bf16_f32 v57, v62, v63
	v_pk_mul_f32 v[54:55], v[54:55], v[66:67] op_sel_hi:[1,0]
	v_cvt_pk_bf16_f32 v58, v58, v59
	v_cvt_pk_bf16_f32 v59, v68, v69
	global_store_dwordx4 v[64:65], v[56:59], off
	v_pk_mul_f32 v[52:53], v[52:53], v[66:67] op_sel_hi:[1,0]
	s_nop 0
	v_pk_mul_f32 v[56:57], v[50:51], v[66:67] op_sel_hi:[1,0]
	v_pk_mul_f32 v[50:51], v[48:49], v[66:67] op_sel_hi:[1,0]
	v_cvt_pk_bf16_f32 v48, v52, v53
	v_cvt_pk_bf16_f32 v49, v54, v55
	s_nop 0
	v_cvt_pk_bf16_f32 v50, v50, v51
	v_cvt_pk_bf16_f32 v51, v56, v57
	global_store_dwordx4 v[64:65], v[48:51], off offset:256
	s_nop 1
	v_mov_b32_e32 v50, v240
	v_pk_mul_f32 v[46:47], v[46:47], v[50:51] op_sel_hi:[1,0]
	v_add_u32_e32 v48, 0x90, v128
	v_mad_i64_i32 v[48:49], s[4:5], v48, s0, v[130:131]
	v_lshl_add_u64 v[48:49], v[48:49], 0, v[132:133]
	v_pk_mul_f32 v[44:45], v[44:45], v[50:51] op_sel_hi:[1,0]
	v_pk_mul_f32 v[52:53], v[42:43], v[50:51] op_sel_hi:[1,0]
	v_pk_mul_f32 v[42:43], v[40:41], v[50:51] op_sel_hi:[1,0]
	v_cvt_pk_bf16_f32 v40, v44, v45
	v_cvt_pk_bf16_f32 v41, v46, v47
	v_pk_mul_f32 v[38:39], v[38:39], v[50:51] op_sel_hi:[1,0]
	v_cvt_pk_bf16_f32 v42, v42, v43
	v_cvt_pk_bf16_f32 v43, v52, v53
	global_store_dwordx4 v[48:49], v[40:43], off
	v_pk_mul_f32 v[36:37], v[36:37], v[50:51] op_sel_hi:[1,0]
	s_nop 0
	v_pk_mul_f32 v[40:41], v[34:35], v[50:51] op_sel_hi:[1,0]
	v_pk_mul_f32 v[34:35], v[32:33], v[50:51] op_sel_hi:[1,0]
	v_cvt_pk_bf16_f32 v32, v36, v37
	v_cvt_pk_bf16_f32 v33, v38, v39
	s_nop 0
	v_cvt_pk_bf16_f32 v34, v34, v35
	v_cvt_pk_bf16_f32 v35, v40, v41
	global_store_dwordx4 v[48:49], v[32:35], off offset:256
	s_nop 1
	v_mov_b32_e32 v34, v241
	v_pk_mul_f32 v[30:31], v[30:31], v[34:35] op_sel_hi:[1,0]
	v_add_u32_e32 v32, 0xa0, v128
	v_mad_i64_i32 v[32:33], s[4:5], v32, s0, v[130:131]
	v_lshl_add_u64 v[32:33], v[32:33], 0, v[132:133]
	v_pk_mul_f32 v[28:29], v[28:29], v[34:35] op_sel_hi:[1,0]
	v_pk_mul_f32 v[36:37], v[26:27], v[34:35] op_sel_hi:[1,0]
	v_pk_mul_f32 v[26:27], v[24:25], v[34:35] op_sel_hi:[1,0]
	v_cvt_pk_bf16_f32 v24, v28, v29
	v_cvt_pk_bf16_f32 v25, v30, v31
	v_pk_mul_f32 v[22:23], v[22:23], v[34:35] op_sel_hi:[1,0]
	v_cvt_pk_bf16_f32 v26, v26, v27
	v_cvt_pk_bf16_f32 v27, v36, v37
	global_store_dwordx4 v[32:33], v[24:27], off
	v_pk_mul_f32 v[20:21], v[20:21], v[34:35] op_sel_hi:[1,0]
	s_nop 0
	v_pk_mul_f32 v[24:25], v[18:19], v[34:35] op_sel_hi:[1,0]
	v_pk_mul_f32 v[18:19], v[16:17], v[34:35] op_sel_hi:[1,0]
	v_cvt_pk_bf16_f32 v16, v20, v21
	v_cvt_pk_bf16_f32 v17, v22, v23
	s_nop 0
	v_cvt_pk_bf16_f32 v18, v18, v19
	v_cvt_pk_bf16_f32 v19, v24, v25
	global_store_dwordx4 v[32:33], v[16:19], off offset:256
	s_nop 1
	v_mov_b32_e32 v18, v242
	v_pk_mul_f32 v[14:15], v[14:15], v[18:19] op_sel_hi:[1,0]
	v_add_u32_e32 v16, 0xb0, v128
	v_mad_i64_i32 v[16:17], s[0:1], v16, s0, v[130:131]
	v_lshl_add_u64 v[16:17], v[16:17], 0, v[132:133]
	v_pk_mul_f32 v[12:13], v[12:13], v[18:19] op_sel_hi:[1,0]
	v_pk_mul_f32 v[20:21], v[10:11], v[18:19] op_sel_hi:[1,0]
	v_pk_mul_f32 v[10:11], v[8:9], v[18:19] op_sel_hi:[1,0]
	v_cvt_pk_bf16_f32 v8, v12, v13
	v_cvt_pk_bf16_f32 v9, v14, v15
	v_pk_mul_f32 v[6:7], v[6:7], v[18:19] op_sel_hi:[1,0]
	v_cvt_pk_bf16_f32 v10, v10, v11
	v_cvt_pk_bf16_f32 v11, v20, v21
	global_store_dwordx4 v[16:17], v[8:11], off
	v_pk_mul_f32 v[4:5], v[4:5], v[18:19] op_sel_hi:[1,0]
	v_readlane_b32 s0, v235, 41
	v_pk_mul_f32 v[8:9], v[2:3], v[18:19] op_sel_hi:[1,0]
	v_pk_mul_f32 v[2:3], v[0:1], v[18:19] op_sel_hi:[1,0]
	v_cvt_pk_bf16_f32 v0, v4, v5
	v_cvt_pk_bf16_f32 v1, v6, v7
	v_readlane_b32 s1, v235, 42
	v_cvt_pk_bf16_f32 v2, v2, v3
	v_cvt_pk_bf16_f32 v3, v8, v9
	global_store_dwordx4 v[16:17], v[0:3], off offset:256
	s_waitcnt vmcnt(0)
	s_barrier
	s_waitcnt vmcnt(0)
	s_and_b64 vcc, exec, s[0:1]
	s_barrier
	s_cbranch_vccnz .LBB0_1645
	v_mbcnt_lo_u32_b32 v0, -1, 0
	v_mbcnt_hi_u32_b32 v0, -1, v0
	s_nop 0
	v_cmp_eq_u32_e32 vcc, 0, v0
	s_and_saveexec_b64 s[0:1], vcc
	s_cbranch_execz .LBB0_1644
	s_mov_b64 s[6:7], exec
	buffer_wbl2 sc1
	s_waitcnt vmcnt(0)
	s_waitcnt vmcnt(0)
	v_mbcnt_lo_u32_b32 v0, s6, 0
	s_add_u32 s4, s78, 0x3900
	v_mbcnt_hi_u32_b32 v0, s7, v0
	s_addc_u32 s5, s79, 0
	v_cmp_eq_u32_e32 vcc, 0, v0
	s_and_saveexec_b64 s[8:9], vcc
	s_cbranch_execz .LBB0_1635
	s_bcnt1_i32_b64 s6, s[6:7]
	v_mov_b32_e32 v0, 0
	v_mov_b32_e32 v1, s6
	global_atomic_add v0, v1, s[4:5]

.LBB0_2274:
	v_lshl_add_u32 v148, s19, 8, v154
	v_lshl_add_u32 v144, s18, 8, v152
	v_ashrrev_i32_e32 v149, 31, v148
	v_mov_b64_e32 v[146:147], s[52:53]
	v_ashrrev_i32_e32 v145, 31, v144
	v_mad_i64_i32 v[150:151], s[18:19], v144, s39, v[146:147]
	v_lshlrev_b64 v[148:149], 1, v[148:149]
	v_lshl_add_u64 v[158:159], v[150:151], 0, v[148:149]
	v_lshl_add_u64 v[150:151], v[144:145], 2, s[88:89]
	global_load_dword v160, v[150:151], off
	global_load_dword v236, v[150:151], off offset:64
	global_load_dword v237, v[150:151], off offset:128
	global_load_dword v238, v[150:151], off offset:192
	global_load_dword v239, v[150:151], off offset:512
	global_load_dword v240, v[150:151], off offset:576
	global_load_dword v241, v[150:151], off offset:640
	global_load_dword v242, v[150:151], off offset:704
	s_andn2_b64 vcc, exec, s[4:5]
	s_waitcnt vmcnt(0)
	v_pk_mul_f32 v[126:127], v[126:127], v[160:161] op_sel_hi:[1,0]
	v_pk_mul_f32 v[124:125], v[124:125], v[160:161] op_sel_hi:[1,0]
	v_pk_mul_f32 v[162:163], v[122:123], v[160:161] op_sel_hi:[1,0]
	v_pk_mul_f32 v[122:123], v[120:121], v[160:161] op_sel_hi:[1,0]
	v_cvt_pk_bf16_f32 v120, v124, v125
	v_cvt_pk_bf16_f32 v121, v126, v127
	v_pk_mul_f32 v[116:117], v[116:117], v[160:161] op_sel_hi:[1,0]
	v_cvt_pk_bf16_f32 v122, v122, v123
	v_cvt_pk_bf16_f32 v123, v162, v163
	global_store_dwordx4 v[158:159], v[120:123], off
	v_pk_mul_f32 v[118:119], v[118:119], v[160:161] op_sel_hi:[1,0]
	s_nop 0
	v_pk_mul_f32 v[120:121], v[114:115], v[160:161] op_sel_hi:[1,0]
	v_pk_mul_f32 v[114:115], v[112:113], v[160:161] op_sel_hi:[1,0]
	v_cvt_pk_bf16_f32 v112, v116, v117
	v_cvt_pk_bf16_f32 v113, v118, v119
	s_nop 0
	v_cvt_pk_bf16_f32 v114, v114, v115
	v_cvt_pk_bf16_f32 v115, v120, v121
	global_store_dwordx4 v[158:159], v[112:115], off offset:256
	s_nop 1
	v_or_b32_e32 v112, 16, v144
	v_ashrrev_i32_e32 v113, 31, v112
	v_mad_i64_i32 v[114:115], s[18:19], v112, s39, v[146:147]
	v_lshl_add_u64 v[112:113], v[112:113], 2, s[88:89]
	v_lshl_add_u64 v[114:115], v[114:115], 0, v[148:149]
	s_nop 1
	v_mov_b32_e32 v112, v236
	v_pk_mul_f32 v[110:111], v[110:111], v[112:113] op_sel_hi:[1,0]
	v_pk_mul_f32 v[108:109], v[108:109], v[112:113] op_sel_hi:[1,0]
	v_pk_mul_f32 v[116:117], v[106:107], v[112:113] op_sel_hi:[1,0]
	v_pk_mul_f32 v[106:107], v[104:105], v[112:113] op_sel_hi:[1,0]
	v_cvt_pk_bf16_f32 v104, v108, v109
	v_cvt_pk_bf16_f32 v105, v110, v111
	v_pk_mul_f32 v[100:101], v[100:101], v[112:113] op_sel_hi:[1,0]
	v_cvt_pk_bf16_f32 v106, v106, v107
	v_cvt_pk_bf16_f32 v107, v116, v117
	global_store_dwordx4 v[114:115], v[104:107], off
	v_pk_mul_f32 v[102:103], v[102:103], v[112:113] op_sel_hi:[1,0]
	s_nop 0
	v_pk_mul_f32 v[104:105], v[98:99], v[112:113] op_sel_hi:[1,0]
	v_pk_mul_f32 v[98:99], v[96:97], v[112:113] op_sel_hi:[1,0]
	v_cvt_pk_bf16_f32 v96, v100, v101
	v_cvt_pk_bf16_f32 v97, v102, v103
	s_nop 0
	v_cvt_pk_bf16_f32 v98, v98, v99
	v_cvt_pk_bf16_f32 v99, v104, v105
	global_store_dwordx4 v[114:115], v[96:99], off offset:256
	s_nop 1
	v_or_b32_e32 v96, 32, v144
	v_ashrrev_i32_e32 v97, 31, v96
	v_mad_i64_i32 v[98:99], s[18:19], v96, s39, v[146:147]
	v_lshl_add_u64 v[96:97], v[96:97], 2, s[88:89]
	v_lshl_add_u64 v[98:99], v[98:99], 0, v[148:149]
	s_nop 1
	v_mov_b32_e32 v96, v237
	v_pk_mul_f32 v[94:95], v[94:95], v[96:97] op_sel_hi:[1,0]
	v_pk_mul_f32 v[92:93], v[92:93], v[96:97] op_sel_hi:[1,0]
	v_pk_mul_f32 v[100:101], v[90:91], v[96:97] op_sel_hi:[1,0]
	v_pk_mul_f32 v[90:91], v[88:89], v[96:97] op_sel_hi:[1,0]
	v_cvt_pk_bf16_f32 v88, v92, v93
	v_cvt_pk_bf16_f32 v89, v94, v95
	v_pk_mul_f32 v[84:85], v[84:85], v[96:97] op_sel_hi:[1,0]
	v_cvt_pk_bf16_f32 v90, v90, v91
	v_cvt_pk_bf16_f32 v91, v100, v101
	global_store_dwordx4 v[98:99], v[88:91], off
	v_pk_mul_f32 v[86:87], v[86:87], v[96:97] op_sel_hi:[1,0]
	s_nop 0
	v_pk_mul_f32 v[88:89], v[82:83], v[96:97] op_sel_hi:[1,0]
	v_pk_mul_f32 v[82:83], v[80:81], v[96:97] op_sel_hi:[1,0]
	v_cvt_pk_bf16_f32 v80, v84, v85
	v_cvt_pk_bf16_f32 v81, v86, v87
	s_nop 0
	v_cvt_pk_bf16_f32 v82, v82, v83
	v_cvt_pk_bf16_f32 v83, v88, v89
	global_store_dwordx4 v[98:99], v[80:83], off offset:256
	s_nop 1
	v_or_b32_e32 v80, 48, v144
	v_ashrrev_i32_e32 v81, 31, v80
	v_mad_i64_i32 v[82:83], s[18:19], v80, s39, v[146:147]
	v_lshl_add_u64 v[80:81], v[80:81], 2, s[88:89]
	v_lshl_add_u64 v[82:83], v[82:83], 0, v[148:149]
	s_nop 1
	v_mov_b32_e32 v80, v238
	v_pk_mul_f32 v[78:79], v[78:79], v[80:81] op_sel_hi:[1,0]
	v_pk_mul_f32 v[76:77], v[76:77], v[80:81] op_sel_hi:[1,0]
	v_pk_mul_f32 v[84:85], v[74:75], v[80:81] op_sel_hi:[1,0]
	v_pk_mul_f32 v[74:75], v[72:73], v[80:81] op_sel_hi:[1,0]
	v_cvt_pk_bf16_f32 v72, v76, v77
	v_cvt_pk_bf16_f32 v73, v78, v79
	v_pk_mul_f32 v[70:71], v[70:71], v[80:81] op_sel_hi:[1,0]
	v_cvt_pk_bf16_f32 v74, v74, v75
	v_cvt_pk_bf16_f32 v75, v84, v85
	global_store_dwordx4 v[82:83], v[72:75], off
	v_pk_mul_f32 v[68:69], v[68:69], v[80:81] op_sel_hi:[1,0]
	s_nop 0
	v_pk_mul_f32 v[72:73], v[66:67], v[80:81] op_sel_hi:[1,0]
	v_pk_mul_f32 v[66:67], v[64:65], v[80:81] op_sel_hi:[1,0]
	v_cvt_pk_bf16_f32 v64, v68, v69
	v_cvt_pk_bf16_f32 v65, v70, v71
	s_nop 0
	v_cvt_pk_bf16_f32 v66, v66, v67
	v_cvt_pk_bf16_f32 v67, v72, v73
	global_store_dwordx4 v[82:83], v[64:67], off offset:256
	s_nop 1
	v_mov_b32_e32 v66, v239
	v_pk_mul_f32 v[62:63], v[62:63], v[66:67] op_sel_hi:[1,0]
	v_add_u32_e32 v64, 0x80, v144
	v_mad_i64_i32 v[64:65], s[18:19], v64, s39, v[146:147]
	v_lshl_add_u64 v[64:65], v[64:65], 0, v[148:149]
	v_pk_mul_f32 v[60:61], v[60:61], v[66:67] op_sel_hi:[1,0]
	v_pk_mul_f32 v[68:69], v[58:59], v[66:67] op_sel_hi:[1,0]
	v_pk_mul_f32 v[58:59], v[56:57], v[66:67] op_sel_hi:[1,0]
	v_cvt_pk_bf16_f32 v56, v60, v61
	v_cvt_pk_bf16_f32 v57, v62, v63
	v_pk_mul_f32 v[54:55], v[54:55], v[66:67] op_sel_hi:[1,0]
	v_cvt_pk_bf16_f32 v58, v58, v59
	v_cvt_pk_bf16_f32 v59, v68, v69
	global_store_dwordx4 v[64:65], v[56:59], off
	v_pk_mul_f32 v[52:53], v[52:53], v[66:67] op_sel_hi:[1,0]
	s_nop 0
	v_pk_mul_f32 v[56:57], v[50:51], v[66:67] op_sel_hi:[1,0]
	v_pk_mul_f32 v[50:51], v[48:49], v[66:67] op_sel_hi:[1,0]
	v_cvt_pk_bf16_f32 v48, v52, v53
	v_cvt_pk_bf16_f32 v49, v54, v55
	s_nop 0
	v_cvt_pk_bf16_f32 v50, v50, v51
	v_cvt_pk_bf16_f32 v51, v56, v57
	global_store_dwordx4 v[64:65], v[48:51], off offset:256
	s_nop 1
	v_mov_b32_e32 v50, v240
	v_pk_mul_f32 v[46:47], v[46:47], v[50:51] op_sel_hi:[1,0]
	v_add_u32_e32 v48, 0x90, v144
	v_mad_i64_i32 v[48:49], s[18:19], v48, s39, v[146:147]
	v_lshl_add_u64 v[48:49], v[48:49], 0, v[148:149]
	v_pk_mul_f32 v[44:45], v[44:45], v[50:51] op_sel_hi:[1,0]
	v_pk_mul_f32 v[52:53], v[42:43], v[50:51] op_sel_hi:[1,0]
	v_pk_mul_f32 v[42:43], v[40:41], v[50:51] op_sel_hi:[1,0]
	v_cvt_pk_bf16_f32 v40, v44, v45
	v_cvt_pk_bf16_f32 v41, v46, v47
	v_pk_mul_f32 v[38:39], v[38:39], v[50:51] op_sel_hi:[1,0]
	v_cvt_pk_bf16_f32 v42, v42, v43
	v_cvt_pk_bf16_f32 v43, v52, v53
	global_store_dwordx4 v[48:49], v[40:43], off
	v_pk_mul_f32 v[36:37], v[36:37], v[50:51] op_sel_hi:[1,0]
	s_nop 0
	v_pk_mul_f32 v[40:41], v[34:35], v[50:51] op_sel_hi:[1,0]
	v_pk_mul_f32 v[34:35], v[32:33], v[50:51] op_sel_hi:[1,0]
	v_cvt_pk_bf16_f32 v32, v36, v37
	v_cvt_pk_bf16_f32 v33, v38, v39
	s_nop 0
	v_cvt_pk_bf16_f32 v34, v34, v35
	v_cvt_pk_bf16_f32 v35, v40, v41
	global_store_dwordx4 v[48:49], v[32:35], off offset:256
	s_nop 1
	v_mov_b32_e32 v34, v241
	v_pk_mul_f32 v[30:31], v[30:31], v[34:35] op_sel_hi:[1,0]
	v_add_u32_e32 v32, 0xa0, v144
	v_mad_i64_i32 v[32:33], s[18:19], v32, s39, v[146:147]
	v_lshl_add_u64 v[32:33], v[32:33], 0, v[148:149]
	v_pk_mul_f32 v[28:29], v[28:29], v[34:35] op_sel_hi:[1,0]
	v_pk_mul_f32 v[36:37], v[26:27], v[34:35] op_sel_hi:[1,0]
	v_pk_mul_f32 v[26:27], v[24:25], v[34:35] op_sel_hi:[1,0]
	v_cvt_pk_bf16_f32 v24, v28, v29
	v_cvt_pk_bf16_f32 v25, v30, v31
	v_pk_mul_f32 v[22:23], v[22:23], v[34:35] op_sel_hi:[1,0]
	v_cvt_pk_bf16_f32 v26, v26, v27
	v_cvt_pk_bf16_f32 v27, v36, v37
	global_store_dwordx4 v[32:33], v[24:27], off
	v_pk_mul_f32 v[20:21], v[20:21], v[34:35] op_sel_hi:[1,0]
	s_nop 0
	v_pk_mul_f32 v[24:25], v[18:19], v[34:35] op_sel_hi:[1,0]
	v_pk_mul_f32 v[18:19], v[16:17], v[34:35] op_sel_hi:[1,0]
	v_cvt_pk_bf16_f32 v16, v20, v21
	v_cvt_pk_bf16_f32 v17, v22, v23
	s_nop 0
	v_cvt_pk_bf16_f32 v18, v18, v19
	v_cvt_pk_bf16_f32 v19, v24, v25
	global_store_dwordx4 v[32:33], v[16:19], off offset:256
	s_nop 1
	v_mov_b32_e32 v18, v242
	v_pk_mul_f32 v[14:15], v[14:15], v[18:19] op_sel_hi:[1,0]
	v_add_u32_e32 v16, 0xb0, v144
	v_mad_i64_i32 v[16:17], s[18:19], v16, s39, v[146:147]
	v_lshl_add_u64 v[16:17], v[16:17], 0, v[148:149]
	v_pk_mul_f32 v[12:13], v[12:13], v[18:19] op_sel_hi:[1,0]
	v_pk_mul_f32 v[20:21], v[10:11], v[18:19] op_sel_hi:[1,0]
	v_pk_mul_f32 v[10:11], v[8:9], v[18:19] op_sel_hi:[1,0]
	v_cvt_pk_bf16_f32 v8, v12, v13
	v_cvt_pk_bf16_f32 v9, v14, v15
	s_mov_b64 s[18:19], -1
	v_cvt_pk_bf16_f32 v10, v10, v11
	v_cvt_pk_bf16_f32 v11, v20, v21
	global_store_dwordx4 v[16:17], v[8:11], off
	v_pk_mul_f32 v[6:7], v[6:7], v[18:19] op_sel_hi:[1,0]
	v_pk_mul_f32 v[4:5], v[4:5], v[18:19] op_sel_hi:[1,0]
	v_pk_mul_f32 v[8:9], v[2:3], v[18:19] op_sel_hi:[1,0]
	v_pk_mul_f32 v[2:3], v[0:1], v[18:19] op_sel_hi:[1,0]
	v_cvt_pk_bf16_f32 v0, v4, v5
	v_cvt_pk_bf16_f32 v1, v6, v7
	s_nop 0
	v_cvt_pk_bf16_f32 v2, v2, v3
	v_cvt_pk_bf16_f32 v3, v8, v9
	global_store_dwordx4 v[16:17], v[0:3], off offset:256
	s_cbranch_vccnz .LBB0_2265
	s_andn2_b64 vcc, exec, s[0:1]
	s_cbranch_vccnz .LBB0_2264
	s_barrier
	s_branch .LBB0_2264

.LBB0_2340:
	v_lshl_add_u32 v128, s4, 8, v141
	v_ashrrev_i32_e32 v129, 31, v128
	v_lshl_add_u64 v[130:131], v[128:129], 2, s[88:89]
	global_load_dword v136, v[130:131], off
	global_load_dword v236, v[130:131], off offset:64
	global_load_dword v237, v[130:131], off offset:128
	global_load_dword v238, v[130:131], off offset:192
	global_load_dword v239, v[130:131], off offset:512
	global_load_dword v240, v[130:131], off offset:576
	global_load_dword v241, v[130:131], off offset:640
	global_load_dword v242, v[130:131], off offset:704
	v_ashrrev_i32_e32 v129, 1, v140
	s_lshl_b32 s1, s0, 8
	v_readlane_b32 s4, v235, 37
	v_and_b32_e32 v129, -8, v129
	s_or_b32 s1, s4, s1
	v_add_u32_e32 v134, s1, v129
	s_movk_i32 s0, 0x1040
	v_mov_b64_e32 v[132:133], s[52:53]
	v_ashrrev_i32_e32 v135, 31, v134
	v_mad_i64_i32 v[138:139], s[4:5], v128, s0, v[132:133]
	v_or_b32_e32 v140, 16, v128
	v_lshlrev_b64 v[134:135], 1, v[134:135]
	v_ashrrev_i32_e32 v141, 31, v140
	v_lshl_add_u64 v[138:139], v[138:139], 0, v[134:135]
	v_lshl_add_u64 v[142:143], v[140:141], 2, s[88:89]
	s_waitcnt vmcnt(0)
	v_pk_mul_f32 v[126:127], v[126:127], v[136:137] op_sel_hi:[1,0]
	v_pk_mul_f32 v[124:125], v[124:125], v[136:137] op_sel_hi:[1,0]
	v_pk_mul_f32 v[122:123], v[122:123], v[136:137] op_sel_hi:[1,0]
	v_pk_mul_f32 v[120:121], v[120:121], v[136:137] op_sel_hi:[1,0]
	v_pk_mul_f32 v[118:119], v[118:119], v[136:137] op_sel_hi:[1,0]
	v_pk_mul_f32 v[116:117], v[116:117], v[136:137] op_sel_hi:[1,0]
	v_pk_mul_f32 v[144:145], v[114:115], v[136:137] op_sel_hi:[1,0]
	v_pk_mul_f32 v[136:137], v[112:113], v[136:137] op_sel_hi:[1,0]
	v_cvt_pk_bf16_f32 v112, v124, v125
	v_cvt_pk_bf16_f32 v113, v126, v127
	v_cvt_pk_bf16_f32 v114, v120, v121
	v_cvt_pk_bf16_f32 v115, v122, v123
	global_store_dwordx4 v[138:139], v[112:115], off
	s_nop 1
	v_cvt_pk_bf16_f32 v112, v116, v117
	v_cvt_pk_bf16_f32 v113, v118, v119
	v_cvt_pk_bf16_f32 v114, v136, v137
	v_cvt_pk_bf16_f32 v115, v144, v145
	global_store_dwordx4 v[138:139], v[112:115], off offset:256
	v_mad_i64_i32 v[116:117], s[4:5], v140, s0, v[132:133]
	v_or_b32_e32 v114, 32, v128
	v_ashrrev_i32_e32 v115, 31, v114
	v_lshl_add_u64 v[116:117], v[116:117], 0, v[134:135]
	v_lshl_add_u64 v[118:119], v[114:115], 2, s[88:89]
	s_nop 1
	v_mov_b32_e32 v112, v236
	v_pk_mul_f32 v[110:111], v[110:111], v[112:113] op_sel_hi:[1,0]
	v_pk_mul_f32 v[108:109], v[108:109], v[112:113] op_sel_hi:[1,0]
	v_pk_mul_f32 v[106:107], v[106:107], v[112:113] op_sel_hi:[1,0]
	v_pk_mul_f32 v[104:105], v[104:105], v[112:113] op_sel_hi:[1,0]
	v_pk_mul_f32 v[102:103], v[102:103], v[112:113] op_sel_hi:[1,0]
	v_pk_mul_f32 v[100:101], v[100:101], v[112:113] op_sel_hi:[1,0]
	v_pk_mul_f32 v[120:121], v[98:99], v[112:113] op_sel_hi:[1,0]
	v_pk_mul_f32 v[112:113], v[96:97], v[112:113] op_sel_hi:[1,0]
	v_cvt_pk_bf16_f32 v96, v108, v109
	v_cvt_pk_bf16_f32 v97, v110, v111
	v_cvt_pk_bf16_f32 v98, v104, v105
	v_cvt_pk_bf16_f32 v99, v106, v107
	global_store_dwordx4 v[116:117], v[96:99], off
	s_nop 1
	v_cvt_pk_bf16_f32 v96, v100, v101
	v_cvt_pk_bf16_f32 v97, v102, v103
	v_cvt_pk_bf16_f32 v98, v112, v113
	v_cvt_pk_bf16_f32 v99, v120, v121
	global_store_dwordx4 v[116:117], v[96:99], off offset:256
	v_mad_i64_i32 v[100:101], s[4:5], v114, s0, v[132:133]
	v_or_b32_e32 v98, 48, v128
	v_ashrrev_i32_e32 v99, 31, v98
	v_lshl_add_u64 v[100:101], v[100:101], 0, v[134:135]
	v_lshl_add_u64 v[102:103], v[98:99], 2, s[88:89]
	s_nop 1
	v_mov_b32_e32 v96, v237
	v_pk_mul_f32 v[94:95], v[94:95], v[96:97] op_sel_hi:[1,0]
	v_pk_mul_f32 v[92:93], v[92:93], v[96:97] op_sel_hi:[1,0]
	v_pk_mul_f32 v[90:91], v[90:91], v[96:97] op_sel_hi:[1,0]
	v_pk_mul_f32 v[88:89], v[88:89], v[96:97] op_sel_hi:[1,0]
	v_pk_mul_f32 v[82:83], v[82:83], v[96:97] op_sel_hi:[1,0]
	v_pk_mul_f32 v[80:81], v[80:81], v[96:97] op_sel_hi:[1,0]
	v_pk_mul_f32 v[104:105], v[74:75], v[96:97] op_sel_hi:[1,0]
	v_pk_mul_f32 v[96:97], v[72:73], v[96:97] op_sel_hi:[1,0]
	v_cvt_pk_bf16_f32 v72, v92, v93
	v_cvt_pk_bf16_f32 v73, v94, v95
	v_cvt_pk_bf16_f32 v74, v88, v89
	v_cvt_pk_bf16_f32 v75, v90, v91
	global_store_dwordx4 v[100:101], v[72:75], off
	s_nop 1
	v_cvt_pk_bf16_f32 v72, v80, v81
	v_cvt_pk_bf16_f32 v73, v82, v83
	v_cvt_pk_bf16_f32 v74, v96, v97
	v_cvt_pk_bf16_f32 v75, v104, v105
	global_store_dwordx4 v[100:101], v[72:75], off offset:256
	s_nop 1
	v_mov_b32_e32 v72, v238
	v_pk_mul_f32 v[80:81], v[86:87], v[72:73] op_sel_hi:[1,0]
	v_mad_i64_i32 v[74:75], s[4:5], v98, s0, v[132:133]
	v_lshl_add_u64 v[74:75], v[74:75], 0, v[134:135]
	v_pk_mul_f32 v[82:83], v[84:85], v[72:73] op_sel_hi:[1,0]
	v_pk_mul_f32 v[78:79], v[78:79], v[72:73] op_sel_hi:[1,0]
	v_pk_mul_f32 v[76:77], v[76:77], v[72:73] op_sel_hi:[1,0]
	v_pk_mul_f32 v[70:71], v[70:71], v[72:73] op_sel_hi:[1,0]
	v_pk_mul_f32 v[68:69], v[68:69], v[72:73] op_sel_hi:[1,0]
	v_pk_mul_f32 v[84:85], v[66:67], v[72:73] op_sel_hi:[1,0]
	v_pk_mul_f32 v[72:73], v[64:65], v[72:73] op_sel_hi:[1,0]
	v_cvt_pk_bf16_f32 v64, v82, v83
	v_cvt_pk_bf16_f32 v65, v80, v81
	v_cvt_pk_bf16_f32 v66, v76, v77
	v_cvt_pk_bf16_f32 v67, v78, v79
	global_store_dwordx4 v[74:75], v[64:67], off
	s_nop 1
	v_cvt_pk_bf16_f32 v64, v68, v69
	v_cvt_pk_bf16_f32 v65, v70, v71
	v_cvt_pk_bf16_f32 v66, v72, v73
	v_cvt_pk_bf16_f32 v67, v84, v85
	global_store_dwordx4 v[74:75], v[64:67], off offset:256
	s_nop 0
	v_add_u32_e32 v65, 0x80, v128
	v_mad_i64_i32 v[66:67], s[4:5], v65, s0, v[132:133]
	v_lshl_add_u64 v[66:67], v[66:67], 0, v[134:135]
	s_nop 1
	v_mov_b32_e32 v64, v239
	v_pk_mul_f32 v[62:63], v[62:63], v[64:65] op_sel_hi:[1,0]
	v_pk_mul_f32 v[60:61], v[60:61], v[64:65] op_sel_hi:[1,0]
	v_pk_mul_f32 v[58:59], v[58:59], v[64:65] op_sel_hi:[1,0]
	v_pk_mul_f32 v[56:57], v[56:57], v[64:65] op_sel_hi:[1,0]
	v_pk_mul_f32 v[54:55], v[54:55], v[64:65] op_sel_hi:[1,0]
	v_pk_mul_f32 v[52:53], v[52:53], v[64:65] op_sel_hi:[1,0]
	v_pk_mul_f32 v[68:69], v[50:51], v[64:65] op_sel_hi:[1,0]
	v_pk_mul_f32 v[64:65], v[48:49], v[64:65] op_sel_hi:[1,0]
	v_cvt_pk_bf16_f32 v48, v60, v61
	v_cvt_pk_bf16_f32 v49, v62, v63
	v_cvt_pk_bf16_f32 v50, v56, v57
	v_cvt_pk_bf16_f32 v51, v58, v59
	global_store_dwordx4 v[66:67], v[48:51], off
	s_nop 1
	v_cvt_pk_bf16_f32 v48, v52, v53
	v_cvt_pk_bf16_f32 v49, v54, v55
	v_cvt_pk_bf16_f32 v50, v64, v65
	v_cvt_pk_bf16_f32 v51, v68, v69
	global_store_dwordx4 v[66:67], v[48:51], off offset:256
	s_nop 0
	v_add_u32_e32 v49, 0x90, v128
	v_mad_i64_i32 v[50:51], s[4:5], v49, s0, v[132:133]
	v_lshl_add_u64 v[50:51], v[50:51], 0, v[134:135]
	s_nop 1
	v_mov_b32_e32 v48, v240
	v_pk_mul_f32 v[46:47], v[46:47], v[48:49] op_sel_hi:[1,0]
	v_pk_mul_f32 v[44:45], v[44:45], v[48:49] op_sel_hi:[1,0]
	v_pk_mul_f32 v[42:43], v[42:43], v[48:49] op_sel_hi:[1,0]
	v_pk_mul_f32 v[40:41], v[40:41], v[48:49] op_sel_hi:[1,0]
	v_pk_mul_f32 v[38:39], v[38:39], v[48:49] op_sel_hi:[1,0]
	v_pk_mul_f32 v[36:37], v[36:37], v[48:49] op_sel_hi:[1,0]
	v_pk_mul_f32 v[52:53], v[34:35], v[48:49] op_sel_hi:[1,0]
	v_pk_mul_f32 v[48:49], v[32:33], v[48:49] op_sel_hi:[1,0]
	v_cvt_pk_bf16_f32 v32, v44, v45
	v_cvt_pk_bf16_f32 v33, v46, v47
	v_cvt_pk_bf16_f32 v34, v40, v41
	v_cvt_pk_bf16_f32 v35, v42, v43
	global_store_dwordx4 v[50:51], v[32:35], off
	s_nop 1
	v_cvt_pk_bf16_f32 v32, v36, v37
	v_cvt_pk_bf16_f32 v33, v38, v39
	v_cvt_pk_bf16_f32 v34, v48, v49
	v_cvt_pk_bf16_f32 v35, v52, v53
	global_store_dwordx4 v[50:51], v[32:35], off offset:256
	s_nop 0
	v_add_u32_e32 v33, 0xa0, v128
	v_mad_i64_i32 v[34:35], s[4:5], v33, s0, v[132:133]
	v_lshl_add_u64 v[34:35], v[34:35], 0, v[134:135]
	s_nop 1
	v_mov_b32_e32 v32, v241
	v_pk_mul_f32 v[30:31], v[30:31], v[32:33] op_sel_hi:[1,0]
	v_pk_mul_f32 v[28:29], v[28:29], v[32:33] op_sel_hi:[1,0]
	v_pk_mul_f32 v[26:27], v[26:27], v[32:33] op_sel_hi:[1,0]
	v_pk_mul_f32 v[24:25], v[24:25], v[32:33] op_sel_hi:[1,0]
	v_pk_mul_f32 v[22:23], v[22:23], v[32:33] op_sel_hi:[1,0]
	v_pk_mul_f32 v[20:21], v[20:21], v[32:33] op_sel_hi:[1,0]
	v_pk_mul_f32 v[36:37], v[18:19], v[32:33] op_sel_hi:[1,0]
	v_pk_mul_f32 v[32:33], v[16:17], v[32:33] op_sel_hi:[1,0]
	v_cvt_pk_bf16_f32 v16, v28, v29
	v_cvt_pk_bf16_f32 v17, v30, v31
	v_cvt_pk_bf16_f32 v18, v24, v25
	v_cvt_pk_bf16_f32 v19, v26, v27
	global_store_dwordx4 v[34:35], v[16:19], off
	s_nop 1
	v_cvt_pk_bf16_f32 v16, v20, v21
	v_cvt_pk_bf16_f32 v17, v22, v23
	v_cvt_pk_bf16_f32 v18, v32, v33
	v_cvt_pk_bf16_f32 v19, v36, v37
	global_store_dwordx4 v[34:35], v[16:19], off offset:256
	s_nop 0
	v_add_u32_e32 v17, 0xb0, v128
	v_mad_i64_i32 v[18:19], s[0:1], v17, s0, v[132:133]
	v_lshl_add_u64 v[18:19], v[18:19], 0, v[134:135]
	v_readlane_b32 s0, v235, 41
	v_readlane_b32 s1, v235, 42
	s_and_b64 vcc, exec, s[0:1]
	s_nop 1
	v_mov_b32_e32 v16, v242
	v_pk_mul_f32 v[14:15], v[14:15], v[16:17] op_sel_hi:[1,0]
	v_pk_mul_f32 v[12:13], v[12:13], v[16:17] op_sel_hi:[1,0]
	v_pk_mul_f32 v[10:11], v[10:11], v[16:17] op_sel_hi:[1,0]
	v_pk_mul_f32 v[8:9], v[8:9], v[16:17] op_sel_hi:[1,0]
	v_pk_mul_f32 v[6:7], v[6:7], v[16:17] op_sel_hi:[1,0]
	v_pk_mul_f32 v[4:5], v[4:5], v[16:17] op_sel_hi:[1,0]
	v_pk_mul_f32 v[20:21], v[2:3], v[16:17] op_sel_hi:[1,0]
	v_pk_mul_f32 v[16:17], v[0:1], v[16:17] op_sel_hi:[1,0]
	v_cvt_pk_bf16_f32 v0, v12, v13
	v_cvt_pk_bf16_f32 v1, v14, v15
	v_cvt_pk_bf16_f32 v2, v8, v9
	v_cvt_pk_bf16_f32 v3, v10, v11
	global_store_dwordx4 v[18:19], v[0:3], off
	s_nop 1
	v_cvt_pk_bf16_f32 v0, v4, v5
	v_cvt_pk_bf16_f32 v1, v6, v7
	v_cvt_pk_bf16_f32 v2, v16, v17
	v_cvt_pk_bf16_f32 v3, v20, v21
	global_store_dwordx4 v[18:19], v[0:3], off offset:256
	s_waitcnt vmcnt(0)
	s_barrier
	s_waitcnt vmcnt(0)
	s_barrier
	s_cbranch_vccnz .LBB0_2354
	v_mbcnt_lo_u32_b32 v0, -1, 0
	v_mbcnt_hi_u32_b32 v0, -1, v0
	s_nop 0
	v_cmp_eq_u32_e32 vcc, 0, v0
	s_and_saveexec_b64 s[0:1], vcc
	s_cbranch_execz .LBB0_2353
	s_mov_b64 s[6:7], exec
	buffer_wbl2 sc1
	s_waitcnt vmcnt(0)
	s_waitcnt vmcnt(0)
	v_mbcnt_lo_u32_b32 v0, s6, 0
	s_add_u32 s4, s78, 0x3a00
	v_mbcnt_hi_u32_b32 v0, s7, v0
	s_addc_u32 s5, s79, 0
	v_cmp_eq_u32_e32 vcc, 0, v0
	s_and_saveexec_b64 s[8:9], vcc
	s_cbranch_execz .LBB0_2344
	s_bcnt1_i32_b64 s6, s[6:7]
	v_mov_b32_e32 v0, 0
	v_mov_b32_e32 v1, s6
	global_atomic_add v0, v1, s[4:5]

	.amdhsa_kernel _Z14fwd_megakernel4Args
		.amdhsa_group_segment_fixed_size 0
		.amdhsa_private_segment_fixed_size 0
		.amdhsa_kernarg_size 432
		.amdhsa_user_sgpr_count 2
		.amdhsa_user_sgpr_dispatch_ptr 0
		.amdhsa_user_sgpr_queue_ptr 0
		.amdhsa_user_sgpr_kernarg_segment_ptr 1
		.amdhsa_user_sgpr_dispatch_id 0
		.amdhsa_user_sgpr_kernarg_preload_length 0
		.amdhsa_user_sgpr_kernarg_preload_offset 0
		.amdhsa_user_sgpr_private_segment_size 0
		.amdhsa_uses_dynamic_stack 0
		.amdhsa_enable_private_segment 0
		.amdhsa_system_sgpr_workgroup_id_x 1
		.amdhsa_system_sgpr_workgroup_id_y 0
		.amdhsa_system_sgpr_workgroup_id_z 0
		.amdhsa_system_sgpr_workgroup_info 0
		.amdhsa_system_vgpr_workitem_id 2
		.amdhsa_next_free_vgpr 244
		.amdhsa_next_free_sgpr 98
		.amdhsa_accum_offset 244
		.amdhsa_reserve_vcc 1
		.amdhsa_float_round_mode_32 0
		.amdhsa_float_round_mode_16_64 0
		.amdhsa_float_denorm_mode_32 3
		.amdhsa_float_denorm_mode_16_64 3
		.amdhsa_dx10_clamp 1
		.amdhsa_ieee_mode 1
		.amdhsa_fp16_overflow 0
		.amdhsa_tg_split 0
		.amdhsa_exception_fp_ieee_invalid_op 0
		.amdhsa_exception_fp_denorm_src 0
		.amdhsa_exception_fp_ieee_div_zero 0
		.amdhsa_exception_fp_ieee_overflow 0
		.amdhsa_exception_fp_ieee_underflow 0
		.amdhsa_exception_fp_ieee_inexact 0
		.amdhsa_exception_int_div_zero 0
	.end_amdhsa_kernel

amdhsa.kernels:
  - .agpr_count:     0
    .args:
      - .offset:         0
        .size:           176
        .value_kind:     by_value
      - .offset:         176
        .size:           4
        .value_kind:     hidden_block_count_x
      - .offset:         180
        .size:           4
        .value_kind:     hidden_block_count_y
      - .offset:         184
        .size:           4
        .value_kind:     hidden_block_count_z
      - .offset:         188
        .size:           2
        .value_kind:     hidden_group_size_x
      - .offset:         190
        .size:           2
        .value_kind:     hidden_group_size_y
      - .offset:         192
        .size:           2
        .value_kind:     hidden_group_size_z
      - .offset:         194
        .size:           2
        .value_kind:     hidden_remainder_x
      - .offset:         196
        .size:           2
        .value_kind:     hidden_remainder_y
      - .offset:         198
        .size:           2
        .value_kind:     hidden_remainder_z
      - .offset:         216
        .size:           8
        .value_kind:     hidden_global_offset_x
      - .offset:         224
        .size:           8
        .value_kind:     hidden_global_offset_y
      - .offset:         232
        .size:           8
        .value_kind:     hidden_global_offset_z
      - .offset:         240
        .size:           2
        .value_kind:     hidden_grid_dims
      - .offset:         264
        .size:           8
        .value_kind:     hidden_multigrid_sync_arg
      - .offset:         296
        .size:           4
        .value_kind:     hidden_dynamic_lds_size
    .group_segment_fixed_size: 0
    .kernarg_segment_align: 8
    .kernarg_segment_size: 432
    .language:       OpenCL C
    .language_version:
      - 2
      - 0
    .max_flat_workgroup_size: 512
    .name:           _Z14fwd_megakernel4Args
    .private_segment_fixed_size: 0
    .sgpr_count:     104
    .sgpr_spill_count: 89
    .symbol:         _Z14fwd_megakernel4Args.kd
    .uniform_work_group_size: 1
    .uses_dynamic_stack: false
    .vgpr_count:     244
    .vgpr_spill_count: 0
    .wavefront_size: 64
